# GEMM loops: M0-hazard s_nop pads removed by placing the address VALU between the m0 write and the LDS-DMA load (96 sites), on top of v20
# speedup vs baseline: 1.0001x; 1.0001x over previous
.LBB0_294:
	ds_read_b128 v[154:157], v151
	ds_read_b128 v[158:161], v151 offset:1024
	ds_read_b128 v[162:165], v151 offset:2048
	ds_read_b128 v[166:169], v151 offset:3072
	ds_read_b128 v[170:173], v152
	ds_read_b128 v[174:177], v152 offset:1024
	ds_read_b128 v[178:181], v152 offset:2048
	ds_read_b128 v[182:185], v152 offset:3072
	s_add_u32 s26, s24, 0xfffc0080
	s_addc_u32 s27, s25, -1
	s_cmp_eq_u32 s51, 12
	s_cselect_b32 s29, s17, s27
	s_cselect_b32 s28, s47, s26
	s_cselect_b32 s27, s15, s50
	s_cselect_b32 s26, s48, s49
	v_lshl_add_u64 v[146:147], s[24:25], 0, v[138:139]
	s_add_i32 m0, s23, 0xc000
	ds_read_b128 v[186:189], v153
	ds_read_b128 v[190:193], v153 offset:1024
	ds_read_b128 v[194:197], v153 offset:2048
	ds_read_b128 v[198:201], v153 offset:3072
	ds_read_b128 v[202:205], v153 offset:4096
	ds_read_b128 v[206:209], v153 offset:5120
	ds_read_b128 v[210:213], v153 offset:6144
	ds_read_b128 v[214:217], v153 offset:7168
	global_load_lds_dwordx4 v[146:147], off
	s_add_i32 m0, s23, 0xe000
	v_lshl_add_u64 v[146:147], s[24:25], 0, v[140:141]
	global_load_lds_dwordx4 v[146:147], off
	s_waitcnt vmcnt(8)
	s_waitcnt lgkmcnt(0)
	s_barrier
	s_setprio 1
	s_waitcnt lgkmcnt(0)
	v_mfma_f32_16x16x32_bf16 v[126:129], v[154:157], v[186:189], v[126:129]
	v_mfma_f32_16x16x32_bf16 v[122:125], v[162:165], v[186:189], v[122:125]
	v_mfma_f32_16x16x32_bf16 v[110:113], v[154:157], v[194:197], v[110:113]
	v_mfma_f32_16x16x32_bf16 v[106:109], v[162:165], v[194:197], v[106:109]
	v_mfma_f32_16x16x32_bf16 v[94:97], v[154:157], v[202:205], v[94:97]
	v_mfma_f32_16x16x32_bf16 v[90:93], v[162:165], v[202:205], v[90:93]
	v_mfma_f32_16x16x32_bf16 v[78:81], v[154:157], v[210:213], v[78:81]
	v_mfma_f32_16x16x32_bf16 v[74:77], v[162:165], v[210:213], v[74:77]
	v_mfma_f32_16x16x32_bf16 v[126:129], v[158:161], v[190:193], v[126:129]
	v_mfma_f32_16x16x32_bf16 v[122:125], v[166:169], v[190:193], v[122:125]
	v_mfma_f32_16x16x32_bf16 v[110:113], v[158:161], v[198:201], v[110:113]
	v_mfma_f32_16x16x32_bf16 v[106:109], v[166:169], v[198:201], v[106:109]
	v_mfma_f32_16x16x32_bf16 v[94:97], v[158:161], v[206:209], v[94:97]
	v_mfma_f32_16x16x32_bf16 v[90:93], v[166:169], v[206:209], v[90:93]
	v_mfma_f32_16x16x32_bf16 v[78:81], v[158:161], v[214:217], v[78:81]
	v_mfma_f32_16x16x32_bf16 v[74:77], v[166:169], v[214:217], v[74:77]
	s_setprio 0
	s_setprio 1
	v_mfma_f32_16x16x32_bf16 v[118:121], v[170:173], v[186:189], v[118:121]
	v_mfma_f32_16x16x32_bf16 v[114:117], v[178:181], v[186:189], v[114:117]
	v_mfma_f32_16x16x32_bf16 v[102:105], v[170:173], v[194:197], v[102:105]
	v_mfma_f32_16x16x32_bf16 v[98:101], v[178:181], v[194:197], v[98:101]
	v_mfma_f32_16x16x32_bf16 v[86:89], v[170:173], v[202:205], v[86:89]
	v_mfma_f32_16x16x32_bf16 v[82:85], v[178:181], v[202:205], v[82:85]
	v_mfma_f32_16x16x32_bf16 v[70:73], v[170:173], v[210:213], v[70:73]
	v_mfma_f32_16x16x32_bf16 v[66:69], v[178:181], v[210:213], v[66:69]
	v_mfma_f32_16x16x32_bf16 v[118:121], v[174:177], v[190:193], v[118:121]
	v_mfma_f32_16x16x32_bf16 v[114:117], v[182:185], v[190:193], v[114:117]
	v_mfma_f32_16x16x32_bf16 v[102:105], v[174:177], v[198:201], v[102:105]
	v_mfma_f32_16x16x32_bf16 v[98:101], v[182:185], v[198:201], v[98:101]
	v_mfma_f32_16x16x32_bf16 v[86:89], v[174:177], v[206:209], v[86:89]
	v_mfma_f32_16x16x32_bf16 v[82:85], v[182:185], v[206:209], v[82:85]
	v_mfma_f32_16x16x32_bf16 v[70:73], v[174:177], v[214:217], v[70:73]
	v_mfma_f32_16x16x32_bf16 v[66:69], v[182:185], v[214:217], v[66:69]
	s_setprio 0
	s_barrier
	s_add_i32 s52, s44, s34
	v_lshl_add_u64 v[146:147], s[26:27], 0, v[134:135]
	s_mov_b32 m0, s52
	ds_read_b128 v[186:189], v153 offset:16384
	ds_read_b128 v[190:193], v153 offset:17408
	ds_read_b128 v[194:197], v153 offset:18432
	ds_read_b128 v[198:201], v153 offset:19456
	ds_read_b128 v[202:205], v153 offset:20480
	ds_read_b128 v[206:209], v153 offset:21504
	ds_read_b128 v[210:213], v153 offset:22528
	ds_read_b128 v[214:217], v153 offset:23552
	global_load_lds_dwordx4 v[146:147], off
	s_add_i32 m0, s52, 0x2000
	s_add_u32 s52, s26, 0x40000
	v_lshl_add_u64 v[218:219], s[26:27], 0, v[130:131]
	s_addc_u32 s53, s27, 0
	s_add_i32 s54, s45, s34
	global_load_lds_dwordx4 v[218:219], off
	v_lshl_add_u64 v[220:221], s[52:53], 0, v[134:135]
	s_mov_b32 m0, s54
	v_lshl_add_u64 v[222:223], s[28:29], 0, v[132:133]
	global_load_lds_dwordx4 v[220:221], off
	s_add_i32 m0, s54, 0x2000
	v_lshl_add_u64 v[220:221], s[52:53], 0, v[130:131]
	global_load_lds_dwordx4 v[220:221], off
	s_mov_b32 m0, s23
	v_lshl_add_u64 v[220:221], s[28:29], 0, v[136:137]
	global_load_lds_dwordx4 v[220:221], off
	s_mov_b32 m0, s36
	s_nop 0
	global_load_lds_dwordx4 v[222:223], off
	s_waitcnt vmcnt(8)
	s_waitcnt lgkmcnt(0)
	s_barrier
	s_setprio 1
	s_waitcnt lgkmcnt(0)
	v_mfma_f32_16x16x32_bf16 v[62:65], v[154:157], v[186:189], v[62:65]
	v_mfma_f32_16x16x32_bf16 v[58:61], v[162:165], v[186:189], v[58:61]
	v_mfma_f32_16x16x32_bf16 v[46:49], v[154:157], v[194:197], v[46:49]
	v_mfma_f32_16x16x32_bf16 v[42:45], v[162:165], v[194:197], v[42:45]
	v_mfma_f32_16x16x32_bf16 v[30:33], v[154:157], v[202:205], v[30:33]
	v_mfma_f32_16x16x32_bf16 v[26:29], v[162:165], v[202:205], v[26:29]
	v_mfma_f32_16x16x32_bf16 v[14:17], v[154:157], v[210:213], v[14:17]
	v_mfma_f32_16x16x32_bf16 v[10:13], v[162:165], v[210:213], v[10:13]
	v_mfma_f32_16x16x32_bf16 v[62:65], v[158:161], v[190:193], v[62:65]
	v_mfma_f32_16x16x32_bf16 v[58:61], v[166:169], v[190:193], v[58:61]
	v_mfma_f32_16x16x32_bf16 v[46:49], v[158:161], v[198:201], v[46:49]
	v_mfma_f32_16x16x32_bf16 v[42:45], v[166:169], v[198:201], v[42:45]
	v_mfma_f32_16x16x32_bf16 v[30:33], v[158:161], v[206:209], v[30:33]
	v_mfma_f32_16x16x32_bf16 v[26:29], v[166:169], v[206:209], v[26:29]
	v_mfma_f32_16x16x32_bf16 v[14:17], v[158:161], v[214:217], v[14:17]
	v_mfma_f32_16x16x32_bf16 v[10:13], v[166:169], v[214:217], v[10:13]
	s_setprio 0
	s_setprio 1
	v_mfma_f32_16x16x32_bf16 v[54:57], v[170:173], v[186:189], v[54:57]
	v_mfma_f32_16x16x32_bf16 v[50:53], v[178:181], v[186:189], v[50:53]
	v_mfma_f32_16x16x32_bf16 v[38:41], v[170:173], v[194:197], v[38:41]
	v_mfma_f32_16x16x32_bf16 v[34:37], v[178:181], v[194:197], v[34:37]
	v_mfma_f32_16x16x32_bf16 v[22:25], v[170:173], v[202:205], v[22:25]
	v_mfma_f32_16x16x32_bf16 v[18:21], v[178:181], v[202:205], v[18:21]
	v_mfma_f32_16x16x32_bf16 v[6:9], v[170:173], v[210:213], v[6:9]
	v_mfma_f32_16x16x32_bf16 v[2:5], v[178:181], v[210:213], v[2:5]
	v_mfma_f32_16x16x32_bf16 v[54:57], v[174:177], v[190:193], v[54:57]
	v_mfma_f32_16x16x32_bf16 v[50:53], v[182:185], v[190:193], v[50:53]
	v_mfma_f32_16x16x32_bf16 v[38:41], v[174:177], v[198:201], v[38:41]
	v_mfma_f32_16x16x32_bf16 v[34:37], v[182:185], v[198:201], v[34:37]
	v_mfma_f32_16x16x32_bf16 v[22:25], v[174:177], v[206:209], v[22:25]
	v_mfma_f32_16x16x32_bf16 v[18:21], v[182:185], v[206:209], v[18:21]
	v_mfma_f32_16x16x32_bf16 v[6:9], v[174:177], v[214:217], v[6:9]
	v_mfma_f32_16x16x32_bf16 v[2:5], v[182:185], v[214:217], v[2:5]
	s_setprio 0
	s_barrier
	s_add_i32 s52, 0, 0x18000
	s_add_i32 s53, 0, 0x1c000
	v_add_u32_e32 v166, s52, v149
	v_add_u32_e32 v182, s53, v149
	ds_read_b128 v[154:157], v166
	ds_read_b128 v[158:161], v166 offset:1024
	ds_read_b128 v[162:165], v166 offset:2048
	ds_read_b128 v[166:169], v166 offset:3072
	ds_read_b128 v[170:173], v182
	ds_read_b128 v[174:177], v182 offset:1024
	ds_read_b128 v[178:181], v182 offset:2048
	ds_read_b128 v[182:185], v182 offset:3072
	s_add_u32 s28, s28, 0x40000
	s_addc_u32 s29, s29, 0
	s_mov_b32 m0, s37
	v_lshl_add_u64 v[224:225], s[28:29], 0, v[136:137]
	ds_read_b128 v[186:189], v153 offset:32768
	ds_read_b128 v[190:193], v153 offset:33792
	ds_read_b128 v[194:197], v153 offset:34816
	ds_read_b128 v[198:201], v153 offset:35840
	ds_read_b128 v[202:205], v153 offset:36864
	ds_read_b128 v[206:209], v153 offset:37888
	ds_read_b128 v[210:213], v153 offset:38912
	ds_read_b128 v[214:217], v153 offset:39936
	global_load_lds_dwordx4 v[224:225], off
	s_mov_b32 m0, s38
	v_lshl_add_u64 v[224:225], s[28:29], 0, v[132:133]
	global_load_lds_dwordx4 v[224:225], off
	s_waitcnt vmcnt(8)
	s_waitcnt lgkmcnt(0)
	s_barrier
	s_setprio 1
	s_waitcnt lgkmcnt(0)
	v_mfma_f32_16x16x32_bf16 v[126:129], v[154:157], v[186:189], v[126:129]
	v_mfma_f32_16x16x32_bf16 v[122:125], v[162:165], v[186:189], v[122:125]
	v_mfma_f32_16x16x32_bf16 v[110:113], v[154:157], v[194:197], v[110:113]
	v_mfma_f32_16x16x32_bf16 v[106:109], v[162:165], v[194:197], v[106:109]
	v_mfma_f32_16x16x32_bf16 v[94:97], v[154:157], v[202:205], v[94:97]
	v_mfma_f32_16x16x32_bf16 v[90:93], v[162:165], v[202:205], v[90:93]
	v_mfma_f32_16x16x32_bf16 v[78:81], v[154:157], v[210:213], v[78:81]
	v_mfma_f32_16x16x32_bf16 v[74:77], v[162:165], v[210:213], v[74:77]
	v_mfma_f32_16x16x32_bf16 v[126:129], v[158:161], v[190:193], v[126:129]
	v_mfma_f32_16x16x32_bf16 v[122:125], v[166:169], v[190:193], v[122:125]
	v_mfma_f32_16x16x32_bf16 v[110:113], v[158:161], v[198:201], v[110:113]
	v_mfma_f32_16x16x32_bf16 v[106:109], v[166:169], v[198:201], v[106:109]
	v_mfma_f32_16x16x32_bf16 v[94:97], v[158:161], v[206:209], v[94:97]
	v_mfma_f32_16x16x32_bf16 v[90:93], v[166:169], v[206:209], v[90:93]
	v_mfma_f32_16x16x32_bf16 v[78:81], v[158:161], v[214:217], v[78:81]
	v_mfma_f32_16x16x32_bf16 v[74:77], v[166:169], v[214:217], v[74:77]
	s_setprio 0
	s_setprio 1
	v_mfma_f32_16x16x32_bf16 v[118:121], v[170:173], v[186:189], v[118:121]
	v_mfma_f32_16x16x32_bf16 v[114:117], v[178:181], v[186:189], v[114:117]
	v_mfma_f32_16x16x32_bf16 v[102:105], v[170:173], v[194:197], v[102:105]
	v_mfma_f32_16x16x32_bf16 v[98:101], v[178:181], v[194:197], v[98:101]
	v_mfma_f32_16x16x32_bf16 v[86:89], v[170:173], v[202:205], v[86:89]
	v_mfma_f32_16x16x32_bf16 v[82:85], v[178:181], v[202:205], v[82:85]
	v_mfma_f32_16x16x32_bf16 v[70:73], v[170:173], v[210:213], v[70:73]
	v_mfma_f32_16x16x32_bf16 v[66:69], v[178:181], v[210:213], v[66:69]
	v_mfma_f32_16x16x32_bf16 v[118:121], v[174:177], v[190:193], v[118:121]
	v_mfma_f32_16x16x32_bf16 v[114:117], v[182:185], v[190:193], v[114:117]
	v_mfma_f32_16x16x32_bf16 v[102:105], v[174:177], v[198:201], v[102:105]
	v_mfma_f32_16x16x32_bf16 v[98:101], v[182:185], v[198:201], v[98:101]
	v_mfma_f32_16x16x32_bf16 v[86:89], v[174:177], v[206:209], v[86:89]
	v_mfma_f32_16x16x32_bf16 v[82:85], v[182:185], v[206:209], v[82:85]
	v_mfma_f32_16x16x32_bf16 v[70:73], v[174:177], v[214:217], v[70:73]
	v_mfma_f32_16x16x32_bf16 v[66:69], v[182:185], v[214:217], v[66:69]
	s_setprio 0
	s_barrier
	s_add_i32 s28, s52, s34
	v_lshl_add_u64 v[146:147], v[146:147], 0, s[10:11]
	s_mov_b32 m0, s28
	ds_read_b128 v[186:189], v153 offset:49152
	ds_read_b128 v[190:193], v153 offset:50176
	ds_read_b128 v[194:197], v153 offset:51200
	ds_read_b128 v[198:201], v153 offset:52224
	ds_read_b128 v[202:205], v153 offset:53248
	ds_read_b128 v[206:209], v153 offset:54272
	ds_read_b128 v[210:213], v153 offset:55296
	ds_read_b128 v[214:217], v153 offset:56320
	global_load_lds_dwordx4 v[146:147], off
	s_add_i32 m0, s28, 0x2000
	s_add_u32 s26, s26, 0x40080
	v_lshl_add_u64 v[146:147], v[218:219], 0, s[10:11]
	s_addc_u32 s27, s27, 0
	s_add_i32 s28, s53, s34
	global_load_lds_dwordx4 v[146:147], off
	s_mov_b32 m0, s28
	v_lshl_add_u64 v[146:147], s[26:27], 0, v[134:135]
	global_load_lds_dwordx4 v[146:147], off
	s_add_i32 m0, s28, 0x2000
	v_lshl_add_u64 v[146:147], s[26:27], 0, v[130:131]
	global_load_lds_dwordx4 v[146:147], off
	s_mov_b32 m0, s41
	v_lshl_add_u64 v[146:147], v[220:221], 0, s[10:11]
	global_load_lds_dwordx4 v[146:147], off
	s_mov_b32 m0, s42
	v_lshl_add_u64 v[146:147], v[222:223], 0, s[10:11]
	global_load_lds_dwordx4 v[146:147], off
	s_waitcnt vmcnt(8)
	s_waitcnt lgkmcnt(0)
	s_barrier
	s_setprio 1
	s_waitcnt lgkmcnt(0)
	v_mfma_f32_16x16x32_bf16 v[62:65], v[154:157], v[186:189], v[62:65]
	v_mfma_f32_16x16x32_bf16 v[58:61], v[162:165], v[186:189], v[58:61]
	v_mfma_f32_16x16x32_bf16 v[46:49], v[154:157], v[194:197], v[46:49]
	v_mfma_f32_16x16x32_bf16 v[42:45], v[162:165], v[194:197], v[42:45]
	v_mfma_f32_16x16x32_bf16 v[30:33], v[154:157], v[202:205], v[30:33]
	v_mfma_f32_16x16x32_bf16 v[26:29], v[162:165], v[202:205], v[26:29]
	v_mfma_f32_16x16x32_bf16 v[14:17], v[154:157], v[210:213], v[14:17]
	v_mfma_f32_16x16x32_bf16 v[10:13], v[162:165], v[210:213], v[10:13]
	v_mfma_f32_16x16x32_bf16 v[62:65], v[158:161], v[190:193], v[62:65]
	v_mfma_f32_16x16x32_bf16 v[58:61], v[166:169], v[190:193], v[58:61]
	v_mfma_f32_16x16x32_bf16 v[46:49], v[158:161], v[198:201], v[46:49]
	v_mfma_f32_16x16x32_bf16 v[42:45], v[166:169], v[198:201], v[42:45]
	v_mfma_f32_16x16x32_bf16 v[30:33], v[158:161], v[206:209], v[30:33]
	v_mfma_f32_16x16x32_bf16 v[26:29], v[166:169], v[206:209], v[26:29]
	v_mfma_f32_16x16x32_bf16 v[14:17], v[158:161], v[214:217], v[14:17]
	v_mfma_f32_16x16x32_bf16 v[10:13], v[166:169], v[214:217], v[10:13]
	s_setprio 0
	s_setprio 1
	v_mfma_f32_16x16x32_bf16 v[54:57], v[170:173], v[186:189], v[54:57]
	v_mfma_f32_16x16x32_bf16 v[50:53], v[178:181], v[186:189], v[50:53]
	v_mfma_f32_16x16x32_bf16 v[38:41], v[170:173], v[194:197], v[38:41]
	v_mfma_f32_16x16x32_bf16 v[34:37], v[178:181], v[194:197], v[34:37]
	v_mfma_f32_16x16x32_bf16 v[22:25], v[170:173], v[202:205], v[22:25]
	v_mfma_f32_16x16x32_bf16 v[18:21], v[178:181], v[202:205], v[18:21]
	v_mfma_f32_16x16x32_bf16 v[6:9], v[170:173], v[210:213], v[6:9]
	v_mfma_f32_16x16x32_bf16 v[2:5], v[178:181], v[210:213], v[2:5]
	v_mfma_f32_16x16x32_bf16 v[54:57], v[174:177], v[190:193], v[54:57]
	v_mfma_f32_16x16x32_bf16 v[50:53], v[182:185], v[190:193], v[50:53]
	v_mfma_f32_16x16x32_bf16 v[38:41], v[174:177], v[198:201], v[38:41]
	v_mfma_f32_16x16x32_bf16 v[34:37], v[182:185], v[198:201], v[34:37]
	v_mfma_f32_16x16x32_bf16 v[22:25], v[174:177], v[206:209], v[22:25]
	v_mfma_f32_16x16x32_bf16 v[18:21], v[182:185], v[206:209], v[18:21]
	v_mfma_f32_16x16x32_bf16 v[6:9], v[174:177], v[214:217], v[6:9]
	v_mfma_f32_16x16x32_bf16 v[2:5], v[182:185], v[214:217], v[2:5]
	s_setprio 0
	s_barrier
	s_add_i32 s51, s51, 2
	s_add_u32 s24, s24, 0x100
	s_addc_u32 s25, s25, 0
	s_add_u32 s49, s49, 0x100
	s_addc_u32 s50, s50, 0
	s_cmp_gt_u32 s51, 13
	s_cbranch_scc0 .LBB0_294
	s_and_b64 vcc, exec, s[12:13]
	s_cbranch_vccz .LBB0_297
	s_barrier

.LBB0_391:
	ds_read_b128 v[158:161], v168
	ds_read_b128 v[162:165], v168 offset:1024
	ds_read_b128 v[172:175], v168 offset:2048
	ds_read_b128 v[176:179], v168 offset:3072
	ds_read_b128 v[180:183], v169
	ds_read_b128 v[184:187], v169 offset:1024
	ds_read_b128 v[188:191], v169 offset:2048
	ds_read_b128 v[192:195], v169 offset:3072
	s_add_u32 s22, s20, 0x100
	s_addc_u32 s23, s21, 0
	s_cmp_eq_u32 s50, 40
	s_cselect_b32 s27, s7, s23
	s_cselect_b32 s26, s6, s22
	s_cselect_b32 s25, s19, s49
	s_cselect_b32 s24, s18, s2
	v_lshl_add_u64 v[228:229], s[20:21], 0, v[136:137]
	s_add_i32 m0, s31, 0xc000
	ds_read_b128 v[196:199], v170
	ds_read_b128 v[200:203], v170 offset:1024
	ds_read_b128 v[204:207], v170 offset:2048
	ds_read_b128 v[208:211], v170 offset:3072
	ds_read_b128 v[212:215], v170 offset:4096
	ds_read_b128 v[216:219], v170 offset:5120
	ds_read_b128 v[220:223], v170 offset:6144
	ds_read_b128 v[224:227], v170 offset:7168
	global_load_lds_dwordx4 v[228:229], off
	s_add_i32 m0, s31, 0xe000
	v_lshl_add_u64 v[228:229], s[20:21], 0, v[138:139]
	global_load_lds_dwordx4 v[228:229], off
	s_waitcnt vmcnt(8)
	s_waitcnt lgkmcnt(0)
	s_barrier
	s_setprio 1
	s_waitcnt lgkmcnt(0)
	v_mfma_f32_16x16x32_bf16 v[126:129], v[158:161], v[196:199], v[126:129]
	v_mfma_f32_16x16x32_bf16 v[122:125], v[172:175], v[196:199], v[122:125]
	v_mfma_f32_16x16x32_bf16 v[114:117], v[158:161], v[204:207], v[114:117]
	v_mfma_f32_16x16x32_bf16 v[110:113], v[172:175], v[204:207], v[110:113]
	v_mfma_f32_16x16x32_bf16 v[98:101], v[158:161], v[212:215], v[98:101]
	v_mfma_f32_16x16x32_bf16 v[94:97], v[172:175], v[212:215], v[94:97]
	v_mfma_f32_16x16x32_bf16 v[82:85], v[158:161], v[220:223], v[82:85]
	v_mfma_f32_16x16x32_bf16 v[78:81], v[172:175], v[220:223], v[78:81]
	v_mfma_f32_16x16x32_bf16 v[126:129], v[162:165], v[200:203], v[126:129]
	v_mfma_f32_16x16x32_bf16 v[122:125], v[176:179], v[200:203], v[122:125]
	v_mfma_f32_16x16x32_bf16 v[114:117], v[162:165], v[208:211], v[114:117]
	v_mfma_f32_16x16x32_bf16 v[110:113], v[176:179], v[208:211], v[110:113]
	v_mfma_f32_16x16x32_bf16 v[98:101], v[162:165], v[216:219], v[98:101]
	v_mfma_f32_16x16x32_bf16 v[94:97], v[176:179], v[216:219], v[94:97]
	v_mfma_f32_16x16x32_bf16 v[82:85], v[162:165], v[224:227], v[82:85]
	v_mfma_f32_16x16x32_bf16 v[78:81], v[176:179], v[224:227], v[78:81]
	s_setprio 0
	s_setprio 1
	v_mfma_f32_16x16x32_bf16 v[118:121], v[180:183], v[196:199], v[118:121]
	v_mfma_f32_16x16x32_bf16 v[106:109], v[188:191], v[196:199], v[106:109]
	v_mfma_f32_16x16x32_bf16 v[102:105], v[180:183], v[204:207], v[102:105]
	v_mfma_f32_16x16x32_bf16 v[90:93], v[188:191], v[204:207], v[90:93]
	v_mfma_f32_16x16x32_bf16 v[86:89], v[180:183], v[212:215], v[86:89]
	v_mfma_f32_16x16x32_bf16 v[74:77], v[188:191], v[212:215], v[74:77]
	v_mfma_f32_16x16x32_bf16 v[70:73], v[180:183], v[220:223], v[70:73]
	v_mfma_f32_16x16x32_bf16 v[66:69], v[188:191], v[220:223], v[66:69]
	v_mfma_f32_16x16x32_bf16 v[118:121], v[184:187], v[200:203], v[118:121]
	v_mfma_f32_16x16x32_bf16 v[106:109], v[192:195], v[200:203], v[106:109]
	v_mfma_f32_16x16x32_bf16 v[102:105], v[184:187], v[208:211], v[102:105]
	v_mfma_f32_16x16x32_bf16 v[90:93], v[192:195], v[208:211], v[90:93]
	v_mfma_f32_16x16x32_bf16 v[86:89], v[184:187], v[216:219], v[86:89]
	v_mfma_f32_16x16x32_bf16 v[74:77], v[192:195], v[216:219], v[74:77]
	v_mfma_f32_16x16x32_bf16 v[70:73], v[184:187], v[224:227], v[70:73]
	v_mfma_f32_16x16x32_bf16 v[66:69], v[192:195], v[224:227], v[66:69]
	s_setprio 0
	s_barrier
	s_add_i32 s20, s43, s30
	v_lshl_add_u64 v[228:229], s[24:25], 0, v[130:131]
	s_mov_b32 m0, s20
	ds_read_b128 v[196:199], v170 offset:16384
	ds_read_b128 v[200:203], v170 offset:17408
	ds_read_b128 v[204:207], v170 offset:18432
	ds_read_b128 v[208:211], v170 offset:19456
	ds_read_b128 v[212:215], v170 offset:20480
	ds_read_b128 v[216:219], v170 offset:21504
	ds_read_b128 v[220:223], v170 offset:22528
	ds_read_b128 v[224:227], v170 offset:23552
	global_load_lds_dwordx4 v[228:229], off
	s_add_i32 m0, s20, 0x2000
	s_add_u32 s20, s24, 0xb0000
	v_lshl_add_u64 v[230:231], s[24:25], 0, v[132:133]
	s_addc_u32 s21, s25, 0
	s_add_i32 s51, s44, s30
	global_load_lds_dwordx4 v[230:231], off
	v_lshl_add_u64 v[232:233], s[20:21], 0, v[130:131]
	s_mov_b32 m0, s51
	v_lshl_add_u64 v[234:235], s[26:27], 0, v[132:133]
	global_load_lds_dwordx4 v[232:233], off
	s_add_i32 m0, s51, 0x2000
	v_lshl_add_u64 v[232:233], s[20:21], 0, v[132:133]
	global_load_lds_dwordx4 v[232:233], off
	s_mov_b32 m0, s31
	v_lshl_add_u64 v[232:233], s[26:27], 0, v[130:131]
	global_load_lds_dwordx4 v[232:233], off
	s_mov_b32 m0, s33
	s_nop 0
	global_load_lds_dwordx4 v[234:235], off
	s_waitcnt vmcnt(8)
	s_waitcnt lgkmcnt(0)
	s_barrier
	s_setprio 1
	s_waitcnt lgkmcnt(0)
	v_mfma_f32_16x16x32_bf16 v[62:65], v[158:161], v[196:199], v[62:65]
	v_mfma_f32_16x16x32_bf16 v[58:61], v[172:175], v[196:199], v[58:61]
	v_mfma_f32_16x16x32_bf16 v[50:53], v[158:161], v[204:207], v[50:53]
	v_mfma_f32_16x16x32_bf16 v[46:49], v[172:175], v[204:207], v[46:49]
	v_mfma_f32_16x16x32_bf16 v[34:37], v[158:161], v[212:215], v[34:37]
	v_mfma_f32_16x16x32_bf16 v[30:33], v[172:175], v[212:215], v[30:33]
	v_mfma_f32_16x16x32_bf16 v[18:21], v[158:161], v[220:223], v[18:21]
	v_mfma_f32_16x16x32_bf16 v[14:17], v[172:175], v[220:223], v[14:17]
	v_mfma_f32_16x16x32_bf16 v[62:65], v[162:165], v[200:203], v[62:65]
	v_mfma_f32_16x16x32_bf16 v[58:61], v[176:179], v[200:203], v[58:61]
	v_mfma_f32_16x16x32_bf16 v[50:53], v[162:165], v[208:211], v[50:53]
	v_mfma_f32_16x16x32_bf16 v[46:49], v[176:179], v[208:211], v[46:49]
	v_mfma_f32_16x16x32_bf16 v[34:37], v[162:165], v[216:219], v[34:37]
	v_mfma_f32_16x16x32_bf16 v[30:33], v[176:179], v[216:219], v[30:33]
	v_mfma_f32_16x16x32_bf16 v[18:21], v[162:165], v[224:227], v[18:21]
	v_mfma_f32_16x16x32_bf16 v[14:17], v[176:179], v[224:227], v[14:17]
	s_setprio 0
	s_setprio 1
	v_mfma_f32_16x16x32_bf16 v[54:57], v[180:183], v[196:199], v[54:57]
	v_mfma_f32_16x16x32_bf16 v[42:45], v[188:191], v[196:199], v[42:45]
	v_mfma_f32_16x16x32_bf16 v[38:41], v[180:183], v[204:207], v[38:41]
	v_mfma_f32_16x16x32_bf16 v[26:29], v[188:191], v[204:207], v[26:29]
	v_mfma_f32_16x16x32_bf16 v[22:25], v[180:183], v[212:215], v[22:25]
	v_mfma_f32_16x16x32_bf16 v[10:13], v[188:191], v[212:215], v[10:13]
	v_mfma_f32_16x16x32_bf16 v[6:9], v[180:183], v[220:223], v[6:9]
	v_mfma_f32_16x16x32_bf16 v[2:5], v[188:191], v[220:223], v[2:5]
	v_mfma_f32_16x16x32_bf16 v[54:57], v[184:187], v[200:203], v[54:57]
	v_mfma_f32_16x16x32_bf16 v[42:45], v[192:195], v[200:203], v[42:45]
	v_mfma_f32_16x16x32_bf16 v[38:41], v[184:187], v[208:211], v[38:41]
	v_mfma_f32_16x16x32_bf16 v[26:29], v[192:195], v[208:211], v[26:29]
	v_mfma_f32_16x16x32_bf16 v[22:25], v[184:187], v[216:219], v[22:25]
	v_mfma_f32_16x16x32_bf16 v[10:13], v[192:195], v[216:219], v[10:13]
	v_mfma_f32_16x16x32_bf16 v[6:9], v[184:187], v[224:227], v[6:9]
	v_mfma_f32_16x16x32_bf16 v[2:5], v[192:195], v[224:227], v[2:5]
	s_setprio 0
	s_barrier
	s_add_i32 s51, 0, 0x18000
	v_add_u32_e32 v171, s51, v166
	s_add_i32 s52, 0, 0x1c000
	ds_read_b128 v[158:161], v171
	ds_read_b128 v[162:165], v171 offset:1024
	ds_read_b128 v[172:175], v171 offset:2048
	ds_read_b128 v[176:179], v171 offset:3072
	v_add_u32_e32 v171, s52, v166
	ds_read_b128 v[180:183], v171
	ds_read_b128 v[184:187], v171 offset:1024
	ds_read_b128 v[188:191], v171 offset:2048
	ds_read_b128 v[192:195], v171 offset:3072
	s_add_u32 s20, s26, 0xb0000
	s_addc_u32 s21, s27, 0
	s_mov_b32 m0, s34
	v_lshl_add_u64 v[236:237], s[20:21], 0, v[130:131]
	ds_read_b128 v[196:199], v170 offset:32768
	ds_read_b128 v[200:203], v170 offset:33792
	ds_read_b128 v[204:207], v170 offset:34816
	ds_read_b128 v[208:211], v170 offset:35840
	ds_read_b128 v[212:215], v170 offset:36864
	ds_read_b128 v[216:219], v170 offset:37888
	ds_read_b128 v[220:223], v170 offset:38912
	ds_read_b128 v[224:227], v170 offset:39936
	global_load_lds_dwordx4 v[236:237], off
	s_mov_b32 m0, s35
	v_lshl_add_u64 v[236:237], s[20:21], 0, v[132:133]
	global_load_lds_dwordx4 v[236:237], off
	s_waitcnt vmcnt(8)
	s_waitcnt lgkmcnt(0)
	s_barrier
	s_setprio 1
	s_waitcnt lgkmcnt(0)
	v_mfma_f32_16x16x32_bf16 v[126:129], v[158:161], v[196:199], v[126:129]
	v_mfma_f32_16x16x32_bf16 v[122:125], v[172:175], v[196:199], v[122:125]
	v_mfma_f32_16x16x32_bf16 v[114:117], v[158:161], v[204:207], v[114:117]
	v_mfma_f32_16x16x32_bf16 v[110:113], v[172:175], v[204:207], v[110:113]
	v_mfma_f32_16x16x32_bf16 v[98:101], v[158:161], v[212:215], v[98:101]
	v_mfma_f32_16x16x32_bf16 v[94:97], v[172:175], v[212:215], v[94:97]
	v_mfma_f32_16x16x32_bf16 v[82:85], v[158:161], v[220:223], v[82:85]
	v_mfma_f32_16x16x32_bf16 v[78:81], v[172:175], v[220:223], v[78:81]
	v_mfma_f32_16x16x32_bf16 v[126:129], v[162:165], v[200:203], v[126:129]
	v_mfma_f32_16x16x32_bf16 v[122:125], v[176:179], v[200:203], v[122:125]
	v_mfma_f32_16x16x32_bf16 v[114:117], v[162:165], v[208:211], v[114:117]
	v_mfma_f32_16x16x32_bf16 v[110:113], v[176:179], v[208:211], v[110:113]
	v_mfma_f32_16x16x32_bf16 v[98:101], v[162:165], v[216:219], v[98:101]
	v_mfma_f32_16x16x32_bf16 v[94:97], v[176:179], v[216:219], v[94:97]
	v_mfma_f32_16x16x32_bf16 v[82:85], v[162:165], v[224:227], v[82:85]
	v_mfma_f32_16x16x32_bf16 v[78:81], v[176:179], v[224:227], v[78:81]
	s_setprio 0
	s_setprio 1
	v_mfma_f32_16x16x32_bf16 v[118:121], v[180:183], v[196:199], v[118:121]
	v_mfma_f32_16x16x32_bf16 v[106:109], v[188:191], v[196:199], v[106:109]
	v_mfma_f32_16x16x32_bf16 v[102:105], v[180:183], v[204:207], v[102:105]
	v_mfma_f32_16x16x32_bf16 v[90:93], v[188:191], v[204:207], v[90:93]
	v_mfma_f32_16x16x32_bf16 v[86:89], v[180:183], v[212:215], v[86:89]
	v_mfma_f32_16x16x32_bf16 v[74:77], v[188:191], v[212:215], v[74:77]
	v_mfma_f32_16x16x32_bf16 v[70:73], v[180:183], v[220:223], v[70:73]
	v_mfma_f32_16x16x32_bf16 v[66:69], v[188:191], v[220:223], v[66:69]
	v_mfma_f32_16x16x32_bf16 v[118:121], v[184:187], v[200:203], v[118:121]
	v_mfma_f32_16x16x32_bf16 v[106:109], v[192:195], v[200:203], v[106:109]
	v_mfma_f32_16x16x32_bf16 v[102:105], v[184:187], v[208:211], v[102:105]
	v_mfma_f32_16x16x32_bf16 v[90:93], v[192:195], v[208:211], v[90:93]
	v_mfma_f32_16x16x32_bf16 v[86:89], v[184:187], v[216:219], v[86:89]
	v_mfma_f32_16x16x32_bf16 v[74:77], v[192:195], v[216:219], v[74:77]
	v_mfma_f32_16x16x32_bf16 v[70:73], v[184:187], v[224:227], v[70:73]
	v_mfma_f32_16x16x32_bf16 v[66:69], v[192:195], v[224:227], v[66:69]
	s_setprio 0
	s_barrier
	s_add_i32 s20, s51, s30
	v_lshl_add_u64 v[228:229], v[228:229], 0, s[14:15]
	s_mov_b32 m0, s20
	ds_read_b128 v[196:199], v170 offset:49152
	ds_read_b128 v[200:203], v170 offset:50176
	ds_read_b128 v[204:207], v170 offset:51200
	ds_read_b128 v[208:211], v170 offset:52224
	ds_read_b128 v[212:215], v170 offset:53248
	ds_read_b128 v[216:219], v170 offset:54272
	ds_read_b128 v[220:223], v170 offset:55296
	ds_read_b128 v[224:227], v170 offset:56320
	global_load_lds_dwordx4 v[228:229], off
	s_add_i32 m0, s20, 0x2000
	s_add_u32 s20, s24, 0xb0080
	v_lshl_add_u64 v[228:229], v[230:231], 0, s[14:15]
	s_addc_u32 s21, s25, 0
	s_add_i32 s24, s52, s30
	global_load_lds_dwordx4 v[228:229], off
	s_mov_b32 m0, s24
	v_lshl_add_u64 v[228:229], s[20:21], 0, v[130:131]
	global_load_lds_dwordx4 v[228:229], off
	s_add_i32 m0, s24, 0x2000
	v_lshl_add_u64 v[228:229], s[20:21], 0, v[132:133]
	global_load_lds_dwordx4 v[228:229], off
	s_mov_b32 m0, s39
	v_lshl_add_u64 v[228:229], v[232:233], 0, s[14:15]
	global_load_lds_dwordx4 v[228:229], off
	s_mov_b32 m0, s40
	v_lshl_add_u64 v[228:229], v[234:235], 0, s[14:15]
	global_load_lds_dwordx4 v[228:229], off
	s_waitcnt vmcnt(8)
	s_waitcnt lgkmcnt(0)
	s_barrier
	s_setprio 1
	s_waitcnt lgkmcnt(0)
	v_mfma_f32_16x16x32_bf16 v[62:65], v[158:161], v[196:199], v[62:65]
	v_mfma_f32_16x16x32_bf16 v[58:61], v[172:175], v[196:199], v[58:61]
	v_mfma_f32_16x16x32_bf16 v[50:53], v[158:161], v[204:207], v[50:53]
	v_mfma_f32_16x16x32_bf16 v[46:49], v[172:175], v[204:207], v[46:49]
	v_mfma_f32_16x16x32_bf16 v[34:37], v[158:161], v[212:215], v[34:37]
	v_mfma_f32_16x16x32_bf16 v[30:33], v[172:175], v[212:215], v[30:33]
	v_mfma_f32_16x16x32_bf16 v[18:21], v[158:161], v[220:223], v[18:21]
	v_mfma_f32_16x16x32_bf16 v[14:17], v[172:175], v[220:223], v[14:17]
	v_mfma_f32_16x16x32_bf16 v[62:65], v[162:165], v[200:203], v[62:65]
	v_mfma_f32_16x16x32_bf16 v[58:61], v[176:179], v[200:203], v[58:61]
	v_mfma_f32_16x16x32_bf16 v[50:53], v[162:165], v[208:211], v[50:53]
	v_mfma_f32_16x16x32_bf16 v[46:49], v[176:179], v[208:211], v[46:49]
	v_mfma_f32_16x16x32_bf16 v[34:37], v[162:165], v[216:219], v[34:37]
	v_mfma_f32_16x16x32_bf16 v[30:33], v[176:179], v[216:219], v[30:33]
	v_mfma_f32_16x16x32_bf16 v[18:21], v[162:165], v[224:227], v[18:21]
	v_mfma_f32_16x16x32_bf16 v[14:17], v[176:179], v[224:227], v[14:17]
	s_setprio 0
	s_setprio 1
	v_mfma_f32_16x16x32_bf16 v[54:57], v[180:183], v[196:199], v[54:57]
	v_mfma_f32_16x16x32_bf16 v[42:45], v[188:191], v[196:199], v[42:45]
	v_mfma_f32_16x16x32_bf16 v[38:41], v[180:183], v[204:207], v[38:41]
	v_mfma_f32_16x16x32_bf16 v[26:29], v[188:191], v[204:207], v[26:29]
	v_mfma_f32_16x16x32_bf16 v[22:25], v[180:183], v[212:215], v[22:25]
	v_mfma_f32_16x16x32_bf16 v[10:13], v[188:191], v[212:215], v[10:13]
	v_mfma_f32_16x16x32_bf16 v[6:9], v[180:183], v[220:223], v[6:9]
	v_mfma_f32_16x16x32_bf16 v[2:5], v[188:191], v[220:223], v[2:5]
	v_mfma_f32_16x16x32_bf16 v[54:57], v[184:187], v[200:203], v[54:57]
	v_mfma_f32_16x16x32_bf16 v[42:45], v[192:195], v[200:203], v[42:45]
	v_mfma_f32_16x16x32_bf16 v[38:41], v[184:187], v[208:211], v[38:41]
	v_mfma_f32_16x16x32_bf16 v[26:29], v[192:195], v[208:211], v[26:29]
	v_mfma_f32_16x16x32_bf16 v[22:25], v[184:187], v[216:219], v[22:25]
	v_mfma_f32_16x16x32_bf16 v[10:13], v[192:195], v[216:219], v[10:13]
	v_mfma_f32_16x16x32_bf16 v[6:9], v[184:187], v[224:227], v[6:9]
	v_mfma_f32_16x16x32_bf16 v[2:5], v[192:195], v[224:227], v[2:5]
	s_setprio 0
	s_barrier
	s_add_i32 s50, s50, 2
	s_add_u32 s2, s2, 0x100
	s_addc_u32 s49, s49, 0
	s_cmp_gt_u32 s50, 41
	s_mov_b64 s[20:21], s[22:23]
	s_cbranch_scc0 .LBB0_391
	s_and_b64 vcc, exec, s[16:17]
	s_cbranch_vccz .LBB0_394
	s_barrier

.LBB0_558:
	ds_read_b128 v[146:149], v153
	ds_read_b128 v[156:159], v153 offset:1024
	ds_read_b128 v[160:163], v153 offset:2048
	ds_read_b128 v[164:167], v153 offset:3072
	ds_read_b128 v[168:171], v154
	ds_read_b128 v[172:175], v154 offset:1024
	ds_read_b128 v[176:179], v154 offset:2048
	ds_read_b128 v[180:183], v154 offset:3072
	s_add_u32 s28, s26, 0xfffc0080
	s_addc_u32 s29, s27, -1
	s_cmp_eq_u32 s52, 12
	s_cselect_b32 s31, s2, s29
	s_cselect_b32 s30, s7, s28
	s_cselect_b32 s29, s17, s51
	s_cselect_b32 s28, s19, s25
	v_lshl_add_u64 v[216:217], s[26:27], 0, v[138:139]
	s_add_i32 m0, s37, 0xc000
	ds_read_b128 v[184:187], v155
	ds_read_b128 v[188:191], v155 offset:1024
	ds_read_b128 v[192:195], v155 offset:2048
	ds_read_b128 v[196:199], v155 offset:3072
	ds_read_b128 v[200:203], v155 offset:4096
	ds_read_b128 v[204:207], v155 offset:5120
	ds_read_b128 v[208:211], v155 offset:6144
	ds_read_b128 v[212:215], v155 offset:7168
	global_load_lds_dwordx4 v[216:217], off
	s_add_i32 m0, s37, 0xe000
	v_lshl_add_u64 v[216:217], s[26:27], 0, v[140:141]
	global_load_lds_dwordx4 v[216:217], off
	s_waitcnt vmcnt(8)
	s_waitcnt lgkmcnt(0)
	s_barrier
	s_setprio 1
	s_waitcnt lgkmcnt(0)
	v_mfma_f32_16x16x32_bf16 v[126:129], v[146:149], v[184:187], v[126:129]
	v_mfma_f32_16x16x32_bf16 v[122:125], v[160:163], v[184:187], v[122:125]
	v_mfma_f32_16x16x32_bf16 v[114:117], v[146:149], v[192:195], v[114:117]
	v_mfma_f32_16x16x32_bf16 v[106:109], v[160:163], v[192:195], v[106:109]
	v_mfma_f32_16x16x32_bf16 v[98:101], v[146:149], v[200:203], v[98:101]
	v_mfma_f32_16x16x32_bf16 v[90:93], v[160:163], v[200:203], v[90:93]
	v_mfma_f32_16x16x32_bf16 v[82:85], v[146:149], v[208:211], v[82:85]
	v_mfma_f32_16x16x32_bf16 v[74:77], v[160:163], v[208:211], v[74:77]
	v_mfma_f32_16x16x32_bf16 v[126:129], v[156:159], v[188:191], v[126:129]
	v_mfma_f32_16x16x32_bf16 v[122:125], v[164:167], v[188:191], v[122:125]
	v_mfma_f32_16x16x32_bf16 v[114:117], v[156:159], v[196:199], v[114:117]
	v_mfma_f32_16x16x32_bf16 v[106:109], v[164:167], v[196:199], v[106:109]
	v_mfma_f32_16x16x32_bf16 v[98:101], v[156:159], v[204:207], v[98:101]
	v_mfma_f32_16x16x32_bf16 v[90:93], v[164:167], v[204:207], v[90:93]
	v_mfma_f32_16x16x32_bf16 v[82:85], v[156:159], v[212:215], v[82:85]
	v_mfma_f32_16x16x32_bf16 v[74:77], v[164:167], v[212:215], v[74:77]
	s_setprio 0
	s_setprio 1
	v_mfma_f32_16x16x32_bf16 v[118:121], v[168:171], v[184:187], v[118:121]
	v_mfma_f32_16x16x32_bf16 v[110:113], v[176:179], v[184:187], v[110:113]
	v_mfma_f32_16x16x32_bf16 v[102:105], v[168:171], v[192:195], v[102:105]
	v_mfma_f32_16x16x32_bf16 v[94:97], v[176:179], v[192:195], v[94:97]
	v_mfma_f32_16x16x32_bf16 v[86:89], v[168:171], v[200:203], v[86:89]
	v_mfma_f32_16x16x32_bf16 v[78:81], v[176:179], v[200:203], v[78:81]
	v_mfma_f32_16x16x32_bf16 v[70:73], v[168:171], v[208:211], v[70:73]
	v_mfma_f32_16x16x32_bf16 v[66:69], v[176:179], v[208:211], v[66:69]
	v_mfma_f32_16x16x32_bf16 v[118:121], v[172:175], v[188:191], v[118:121]
	v_mfma_f32_16x16x32_bf16 v[110:113], v[180:183], v[188:191], v[110:113]
	v_mfma_f32_16x16x32_bf16 v[102:105], v[172:175], v[196:199], v[102:105]
	v_mfma_f32_16x16x32_bf16 v[94:97], v[180:183], v[196:199], v[94:97]
	v_mfma_f32_16x16x32_bf16 v[86:89], v[172:175], v[204:207], v[86:89]
	v_mfma_f32_16x16x32_bf16 v[78:81], v[180:183], v[204:207], v[78:81]
	v_mfma_f32_16x16x32_bf16 v[70:73], v[172:175], v[212:215], v[70:73]
	v_mfma_f32_16x16x32_bf16 v[66:69], v[180:183], v[212:215], v[66:69]
	s_setprio 0
	s_barrier
	s_add_i32 s53, s47, s36
	v_lshl_add_u64 v[216:217], s[28:29], 0, v[132:133]
	s_mov_b32 m0, s53
	ds_read_b128 v[184:187], v155 offset:16384
	ds_read_b128 v[188:191], v155 offset:17408
	ds_read_b128 v[192:195], v155 offset:18432
	ds_read_b128 v[196:199], v155 offset:19456
	ds_read_b128 v[200:203], v155 offset:20480
	ds_read_b128 v[204:207], v155 offset:21504
	ds_read_b128 v[208:211], v155 offset:22528
	ds_read_b128 v[212:215], v155 offset:23552
	global_load_lds_dwordx4 v[216:217], off
	s_add_i32 m0, s53, 0x2000
	s_add_u32 s54, s28, 0x40000
	v_lshl_add_u64 v[218:219], s[28:29], 0, v[136:137]
	s_addc_u32 s55, s29, 0
	s_add_i32 s53, s48, s36
	global_load_lds_dwordx4 v[218:219], off
	v_lshl_add_u64 v[220:221], s[54:55], 0, v[132:133]
	s_mov_b32 m0, s53
	v_lshl_add_u64 v[222:223], s[30:31], 0, v[134:135]
	global_load_lds_dwordx4 v[220:221], off
	s_add_i32 m0, s53, 0x2000
	v_lshl_add_u64 v[220:221], s[54:55], 0, v[136:137]
	global_load_lds_dwordx4 v[220:221], off
	s_mov_b32 m0, s37
	v_lshl_add_u64 v[220:221], s[30:31], 0, v[130:131]
	global_load_lds_dwordx4 v[220:221], off
	s_mov_b32 m0, s38
	s_nop 0
	global_load_lds_dwordx4 v[222:223], off
	s_waitcnt vmcnt(8)
	s_waitcnt lgkmcnt(0)
	s_barrier
	s_setprio 1
	s_waitcnt lgkmcnt(0)
	v_mfma_f32_16x16x32_bf16 v[62:65], v[146:149], v[184:187], v[62:65]
	v_mfma_f32_16x16x32_bf16 v[58:61], v[160:163], v[184:187], v[58:61]
	v_mfma_f32_16x16x32_bf16 v[50:53], v[146:149], v[192:195], v[50:53]
	v_mfma_f32_16x16x32_bf16 v[42:45], v[160:163], v[192:195], v[42:45]
	v_mfma_f32_16x16x32_bf16 v[34:37], v[146:149], v[200:203], v[34:37]
	v_mfma_f32_16x16x32_bf16 v[26:29], v[160:163], v[200:203], v[26:29]
	v_mfma_f32_16x16x32_bf16 v[18:21], v[146:149], v[208:211], v[18:21]
	v_mfma_f32_16x16x32_bf16 v[10:13], v[160:163], v[208:211], v[10:13]
	v_mfma_f32_16x16x32_bf16 v[62:65], v[156:159], v[188:191], v[62:65]
	v_mfma_f32_16x16x32_bf16 v[58:61], v[164:167], v[188:191], v[58:61]
	v_mfma_f32_16x16x32_bf16 v[50:53], v[156:159], v[196:199], v[50:53]
	v_mfma_f32_16x16x32_bf16 v[42:45], v[164:167], v[196:199], v[42:45]
	v_mfma_f32_16x16x32_bf16 v[34:37], v[156:159], v[204:207], v[34:37]
	v_mfma_f32_16x16x32_bf16 v[26:29], v[164:167], v[204:207], v[26:29]
	v_mfma_f32_16x16x32_bf16 v[18:21], v[156:159], v[212:215], v[18:21]
	v_mfma_f32_16x16x32_bf16 v[10:13], v[164:167], v[212:215], v[10:13]
	s_setprio 0
	s_setprio 1
	v_mfma_f32_16x16x32_bf16 v[54:57], v[168:171], v[184:187], v[54:57]
	v_mfma_f32_16x16x32_bf16 v[46:49], v[176:179], v[184:187], v[46:49]
	v_mfma_f32_16x16x32_bf16 v[38:41], v[168:171], v[192:195], v[38:41]
	v_mfma_f32_16x16x32_bf16 v[30:33], v[176:179], v[192:195], v[30:33]
	v_mfma_f32_16x16x32_bf16 v[22:25], v[168:171], v[200:203], v[22:25]
	v_mfma_f32_16x16x32_bf16 v[14:17], v[176:179], v[200:203], v[14:17]
	v_mfma_f32_16x16x32_bf16 v[6:9], v[168:171], v[208:211], v[6:9]
	v_mfma_f32_16x16x32_bf16 v[2:5], v[176:179], v[208:211], v[2:5]
	v_mfma_f32_16x16x32_bf16 v[54:57], v[172:175], v[188:191], v[54:57]
	v_mfma_f32_16x16x32_bf16 v[46:49], v[180:183], v[188:191], v[46:49]
	v_mfma_f32_16x16x32_bf16 v[38:41], v[172:175], v[196:199], v[38:41]
	v_mfma_f32_16x16x32_bf16 v[30:33], v[180:183], v[196:199], v[30:33]
	v_mfma_f32_16x16x32_bf16 v[22:25], v[172:175], v[204:207], v[22:25]
	v_mfma_f32_16x16x32_bf16 v[14:17], v[180:183], v[204:207], v[14:17]
	v_mfma_f32_16x16x32_bf16 v[6:9], v[172:175], v[212:215], v[6:9]
	v_mfma_f32_16x16x32_bf16 v[2:5], v[180:183], v[212:215], v[2:5]
	s_setprio 0
	s_barrier
	s_add_i32 s53, 0, 0x18000
	s_add_i32 s54, 0, 0x1c000
	v_add_u32_e32 v164, s53, v151
	v_add_u32_e32 v180, s54, v151
	ds_read_b128 v[146:149], v164
	ds_read_b128 v[156:159], v164 offset:1024
	ds_read_b128 v[160:163], v164 offset:2048
	ds_read_b128 v[164:167], v164 offset:3072
	ds_read_b128 v[168:171], v180
	ds_read_b128 v[172:175], v180 offset:1024
	ds_read_b128 v[176:179], v180 offset:2048
	ds_read_b128 v[180:183], v180 offset:3072
	s_add_u32 s30, s30, 0x40000
	s_addc_u32 s31, s31, 0
	s_mov_b32 m0, s39
	v_lshl_add_u64 v[224:225], s[30:31], 0, v[130:131]
	ds_read_b128 v[184:187], v155 offset:32768
	ds_read_b128 v[188:191], v155 offset:33792
	ds_read_b128 v[192:195], v155 offset:34816
	ds_read_b128 v[196:199], v155 offset:35840
	ds_read_b128 v[200:203], v155 offset:36864
	ds_read_b128 v[204:207], v155 offset:37888
	ds_read_b128 v[208:211], v155 offset:38912
	ds_read_b128 v[212:215], v155 offset:39936
	global_load_lds_dwordx4 v[224:225], off
	s_mov_b32 m0, s40
	v_lshl_add_u64 v[224:225], s[30:31], 0, v[134:135]
	global_load_lds_dwordx4 v[224:225], off
	s_waitcnt vmcnt(8)
	s_waitcnt lgkmcnt(0)
	s_barrier
	s_setprio 1
	s_waitcnt lgkmcnt(0)
	v_mfma_f32_16x16x32_bf16 v[126:129], v[146:149], v[184:187], v[126:129]
	v_mfma_f32_16x16x32_bf16 v[122:125], v[160:163], v[184:187], v[122:125]
	v_mfma_f32_16x16x32_bf16 v[114:117], v[146:149], v[192:195], v[114:117]
	v_mfma_f32_16x16x32_bf16 v[106:109], v[160:163], v[192:195], v[106:109]
	v_mfma_f32_16x16x32_bf16 v[98:101], v[146:149], v[200:203], v[98:101]
	v_mfma_f32_16x16x32_bf16 v[90:93], v[160:163], v[200:203], v[90:93]
	v_mfma_f32_16x16x32_bf16 v[82:85], v[146:149], v[208:211], v[82:85]
	v_mfma_f32_16x16x32_bf16 v[74:77], v[160:163], v[208:211], v[74:77]
	v_mfma_f32_16x16x32_bf16 v[126:129], v[156:159], v[188:191], v[126:129]
	v_mfma_f32_16x16x32_bf16 v[122:125], v[164:167], v[188:191], v[122:125]
	v_mfma_f32_16x16x32_bf16 v[114:117], v[156:159], v[196:199], v[114:117]
	v_mfma_f32_16x16x32_bf16 v[106:109], v[164:167], v[196:199], v[106:109]
	v_mfma_f32_16x16x32_bf16 v[98:101], v[156:159], v[204:207], v[98:101]
	v_mfma_f32_16x16x32_bf16 v[90:93], v[164:167], v[204:207], v[90:93]
	v_mfma_f32_16x16x32_bf16 v[82:85], v[156:159], v[212:215], v[82:85]
	v_mfma_f32_16x16x32_bf16 v[74:77], v[164:167], v[212:215], v[74:77]
	s_setprio 0
	s_setprio 1
	v_mfma_f32_16x16x32_bf16 v[118:121], v[168:171], v[184:187], v[118:121]
	v_mfma_f32_16x16x32_bf16 v[110:113], v[176:179], v[184:187], v[110:113]
	v_mfma_f32_16x16x32_bf16 v[102:105], v[168:171], v[192:195], v[102:105]
	v_mfma_f32_16x16x32_bf16 v[94:97], v[176:179], v[192:195], v[94:97]
	v_mfma_f32_16x16x32_bf16 v[86:89], v[168:171], v[200:203], v[86:89]
	v_mfma_f32_16x16x32_bf16 v[78:81], v[176:179], v[200:203], v[78:81]
	v_mfma_f32_16x16x32_bf16 v[70:73], v[168:171], v[208:211], v[70:73]
	v_mfma_f32_16x16x32_bf16 v[66:69], v[176:179], v[208:211], v[66:69]
	v_mfma_f32_16x16x32_bf16 v[118:121], v[172:175], v[188:191], v[118:121]
	v_mfma_f32_16x16x32_bf16 v[110:113], v[180:183], v[188:191], v[110:113]
	v_mfma_f32_16x16x32_bf16 v[102:105], v[172:175], v[196:199], v[102:105]
	v_mfma_f32_16x16x32_bf16 v[94:97], v[180:183], v[196:199], v[94:97]
	v_mfma_f32_16x16x32_bf16 v[86:89], v[172:175], v[204:207], v[86:89]
	v_mfma_f32_16x16x32_bf16 v[78:81], v[180:183], v[204:207], v[78:81]
	v_mfma_f32_16x16x32_bf16 v[70:73], v[172:175], v[212:215], v[70:73]
	v_mfma_f32_16x16x32_bf16 v[66:69], v[180:183], v[212:215], v[66:69]
	s_setprio 0
	s_barrier
	s_add_i32 s30, s53, s36
	v_lshl_add_u64 v[216:217], v[216:217], 0, s[12:13]
	s_mov_b32 m0, s30
	ds_read_b128 v[184:187], v155 offset:49152
	ds_read_b128 v[188:191], v155 offset:50176
	ds_read_b128 v[192:195], v155 offset:51200
	ds_read_b128 v[196:199], v155 offset:52224
	ds_read_b128 v[200:203], v155 offset:53248
	ds_read_b128 v[204:207], v155 offset:54272
	ds_read_b128 v[208:211], v155 offset:55296
	ds_read_b128 v[212:215], v155 offset:56320
	global_load_lds_dwordx4 v[216:217], off
	s_add_i32 m0, s30, 0x2000
	s_add_u32 s28, s28, 0x40080
	v_lshl_add_u64 v[216:217], v[218:219], 0, s[12:13]
	s_addc_u32 s29, s29, 0
	s_add_i32 s30, s54, s36
	global_load_lds_dwordx4 v[216:217], off
	s_mov_b32 m0, s30
	v_lshl_add_u64 v[216:217], s[28:29], 0, v[132:133]
	global_load_lds_dwordx4 v[216:217], off
	s_add_i32 m0, s30, 0x2000
	v_lshl_add_u64 v[216:217], s[28:29], 0, v[136:137]
	global_load_lds_dwordx4 v[216:217], off
	s_mov_b32 m0, s42
	v_lshl_add_u64 v[216:217], v[220:221], 0, s[12:13]
	global_load_lds_dwordx4 v[216:217], off
	s_mov_b32 m0, s43
	v_lshl_add_u64 v[216:217], v[222:223], 0, s[12:13]
	global_load_lds_dwordx4 v[216:217], off
	s_waitcnt vmcnt(8)
	s_waitcnt lgkmcnt(0)
	s_barrier
	s_setprio 1
	s_waitcnt lgkmcnt(0)
	v_mfma_f32_16x16x32_bf16 v[62:65], v[146:149], v[184:187], v[62:65]
	v_mfma_f32_16x16x32_bf16 v[58:61], v[160:163], v[184:187], v[58:61]
	v_mfma_f32_16x16x32_bf16 v[50:53], v[146:149], v[192:195], v[50:53]
	v_mfma_f32_16x16x32_bf16 v[42:45], v[160:163], v[192:195], v[42:45]
	v_mfma_f32_16x16x32_bf16 v[34:37], v[146:149], v[200:203], v[34:37]
	v_mfma_f32_16x16x32_bf16 v[26:29], v[160:163], v[200:203], v[26:29]
	v_mfma_f32_16x16x32_bf16 v[18:21], v[146:149], v[208:211], v[18:21]
	v_mfma_f32_16x16x32_bf16 v[10:13], v[160:163], v[208:211], v[10:13]
	v_mfma_f32_16x16x32_bf16 v[62:65], v[156:159], v[188:191], v[62:65]
	v_mfma_f32_16x16x32_bf16 v[58:61], v[164:167], v[188:191], v[58:61]
	v_mfma_f32_16x16x32_bf16 v[50:53], v[156:159], v[196:199], v[50:53]
	v_mfma_f32_16x16x32_bf16 v[42:45], v[164:167], v[196:199], v[42:45]
	v_mfma_f32_16x16x32_bf16 v[34:37], v[156:159], v[204:207], v[34:37]
	v_mfma_f32_16x16x32_bf16 v[26:29], v[164:167], v[204:207], v[26:29]
	v_mfma_f32_16x16x32_bf16 v[18:21], v[156:159], v[212:215], v[18:21]
	v_mfma_f32_16x16x32_bf16 v[10:13], v[164:167], v[212:215], v[10:13]
	s_setprio 0
	s_setprio 1
	v_mfma_f32_16x16x32_bf16 v[54:57], v[168:171], v[184:187], v[54:57]
	v_mfma_f32_16x16x32_bf16 v[46:49], v[176:179], v[184:187], v[46:49]
	v_mfma_f32_16x16x32_bf16 v[38:41], v[168:171], v[192:195], v[38:41]
	v_mfma_f32_16x16x32_bf16 v[30:33], v[176:179], v[192:195], v[30:33]
	v_mfma_f32_16x16x32_bf16 v[22:25], v[168:171], v[200:203], v[22:25]
	v_mfma_f32_16x16x32_bf16 v[14:17], v[176:179], v[200:203], v[14:17]
	v_mfma_f32_16x16x32_bf16 v[6:9], v[168:171], v[208:211], v[6:9]
	v_mfma_f32_16x16x32_bf16 v[2:5], v[176:179], v[208:211], v[2:5]
	v_mfma_f32_16x16x32_bf16 v[54:57], v[172:175], v[188:191], v[54:57]
	v_mfma_f32_16x16x32_bf16 v[46:49], v[180:183], v[188:191], v[46:49]
	v_mfma_f32_16x16x32_bf16 v[38:41], v[172:175], v[196:199], v[38:41]
	v_mfma_f32_16x16x32_bf16 v[30:33], v[180:183], v[196:199], v[30:33]
	v_mfma_f32_16x16x32_bf16 v[22:25], v[172:175], v[204:207], v[22:25]
	v_mfma_f32_16x16x32_bf16 v[14:17], v[180:183], v[204:207], v[14:17]
	v_mfma_f32_16x16x32_bf16 v[6:9], v[172:175], v[212:215], v[6:9]
	v_mfma_f32_16x16x32_bf16 v[2:5], v[180:183], v[212:215], v[2:5]
	s_setprio 0
	s_barrier
	s_add_i32 s52, s52, 2
	s_add_u32 s26, s26, 0x100
	s_addc_u32 s27, s27, 0
	s_add_u32 s25, s25, 0x100
	s_addc_u32 s51, s51, 0
	s_cmp_gt_u32 s52, 13
	s_cbranch_scc0 .LBB0_558
	s_and_b64 vcc, exec, s[14:15]
	s_cbranch_vccz .LBB0_561
	s_barrier

.LBB0_1101:
	ds_read_b128 v[58:61], v178
	ds_read_b128 v[110:113], v178 offset:1024
	ds_read_b128 v[114:117], v178 offset:2048
	ds_read_b128 v[122:125], v178 offset:3072
	ds_read_b128 v[182:185], v179
	ds_read_b128 v[186:189], v179 offset:1024
	ds_read_b128 v[190:193], v179 offset:2048
	ds_read_b128 v[194:197], v179 offset:3072
	s_add_u32 s28, s26, 0x100
	s_addc_u32 s29, s27, 0
	s_cmp_eq_u32 s54, 12
	s_cselect_b32 s35, s2, s29
	s_cselect_b32 s34, s19, s28
	s_cselect_b32 s31, s17, s53
	s_cselect_b32 s30, s51, s52
	v_lshl_add_u64 v[174:175], s[26:27], 0, v[166:167]
	s_add_i32 m0, s38, 0xc000
	ds_read_b128 v[198:201], v180
	ds_read_b128 v[202:205], v180 offset:1024
	ds_read_b128 v[206:209], v180 offset:2048
	ds_read_b128 v[210:213], v180 offset:3072
	ds_read_b128 v[214:217], v180 offset:4096
	ds_read_b128 v[218:221], v180 offset:5120
	ds_read_b128 v[222:225], v180 offset:6144
	ds_read_b128 v[226:229], v180 offset:7168
	global_load_lds_dwordx4 v[174:175], off
	s_add_i32 m0, s38, 0xe000
	v_lshl_add_u64 v[174:175], s[26:27], 0, v[168:169]
	global_load_lds_dwordx4 v[174:175], off
	s_waitcnt vmcnt(8)
	s_waitcnt lgkmcnt(0)
	s_barrier
	s_setprio 1
	s_waitcnt lgkmcnt(0)
	v_mfma_f32_16x16x32_bf16 v[142:145], v[58:61], v[198:201], v[142:145]
	v_mfma_f32_16x16x32_bf16 v[138:141], v[114:117], v[198:201], v[138:141]
	v_mfma_f32_16x16x32_bf16 v[130:133], v[58:61], v[206:209], v[130:133]
	v_mfma_f32_16x16x32_bf16 v[118:121], v[114:117], v[206:209], v[118:121]
	v_mfma_f32_16x16x32_bf16 v[102:105], v[58:61], v[214:217], v[102:105]
	v_mfma_f32_16x16x32_bf16 v[94:97], v[114:117], v[214:217], v[94:97]
	v_mfma_f32_16x16x32_bf16 v[86:89], v[58:61], v[222:225], v[86:89]
	v_mfma_f32_16x16x32_bf16 v[78:81], v[114:117], v[222:225], v[78:81]
	v_mfma_f32_16x16x32_bf16 v[142:145], v[110:113], v[202:205], v[142:145]
	v_mfma_f32_16x16x32_bf16 v[138:141], v[122:125], v[202:205], v[138:141]
	v_mfma_f32_16x16x32_bf16 v[130:133], v[110:113], v[210:213], v[130:133]
	v_mfma_f32_16x16x32_bf16 v[118:121], v[122:125], v[210:213], v[118:121]
	v_mfma_f32_16x16x32_bf16 v[102:105], v[110:113], v[218:221], v[102:105]
	v_mfma_f32_16x16x32_bf16 v[94:97], v[122:125], v[218:221], v[94:97]
	v_mfma_f32_16x16x32_bf16 v[86:89], v[110:113], v[226:229], v[86:89]
	v_mfma_f32_16x16x32_bf16 v[78:81], v[122:125], v[226:229], v[78:81]
	s_setprio 0
	s_setprio 1
	v_mfma_f32_16x16x32_bf16 v[134:137], v[182:185], v[198:201], v[134:137]
	v_mfma_f32_16x16x32_bf16 v[126:129], v[190:193], v[198:201], v[126:129]
	v_mfma_f32_16x16x32_bf16 v[106:109], v[182:185], v[206:209], v[106:109]
	v_mfma_f32_16x16x32_bf16 v[98:101], v[190:193], v[206:209], v[98:101]
	v_mfma_f32_16x16x32_bf16 v[90:93], v[182:185], v[214:217], v[90:93]
	v_mfma_f32_16x16x32_bf16 v[82:85], v[190:193], v[214:217], v[82:85]
	v_mfma_f32_16x16x32_bf16 v[74:77], v[182:185], v[222:225], v[74:77]
	v_mfma_f32_16x16x32_bf16 v[70:73], v[190:193], v[222:225], v[70:73]
	v_mfma_f32_16x16x32_bf16 v[134:137], v[186:189], v[202:205], v[134:137]
	v_mfma_f32_16x16x32_bf16 v[126:129], v[194:197], v[202:205], v[126:129]
	v_mfma_f32_16x16x32_bf16 v[106:109], v[186:189], v[210:213], v[106:109]
	v_mfma_f32_16x16x32_bf16 v[98:101], v[194:197], v[210:213], v[98:101]
	v_mfma_f32_16x16x32_bf16 v[90:93], v[186:189], v[218:221], v[90:93]
	v_mfma_f32_16x16x32_bf16 v[82:85], v[194:197], v[218:221], v[82:85]
	v_mfma_f32_16x16x32_bf16 v[74:77], v[186:189], v[226:229], v[74:77]
	v_mfma_f32_16x16x32_bf16 v[70:73], v[194:197], v[226:229], v[70:73]
	s_setprio 0
	s_barrier
	s_add_i32 s26, s49, s37
	v_lshl_add_u64 v[174:175], s[30:31], 0, v[146:147]
	s_mov_b32 m0, s26
	ds_read_b128 v[198:201], v180 offset:16384
	ds_read_b128 v[202:205], v180 offset:17408
	ds_read_b128 v[206:209], v180 offset:18432
	ds_read_b128 v[210:213], v180 offset:19456
	ds_read_b128 v[214:217], v180 offset:20480
	ds_read_b128 v[218:221], v180 offset:21504
	ds_read_b128 v[222:225], v180 offset:22528
	ds_read_b128 v[226:229], v180 offset:23552
	global_load_lds_dwordx4 v[174:175], off
	s_add_i32 m0, s26, 0x2000
	s_add_u32 s26, s30, 0x40000
	v_lshl_add_u64 v[230:231], s[30:31], 0, v[148:149]
	s_addc_u32 s27, s31, 0
	s_add_i32 s55, s50, s37
	global_load_lds_dwordx4 v[230:231], off
	v_lshl_add_u64 v[232:233], s[26:27], 0, v[146:147]
	s_mov_b32 m0, s55
	v_lshl_add_u64 v[234:235], s[34:35], 0, v[148:149]
	global_load_lds_dwordx4 v[232:233], off
	s_add_i32 m0, s55, 0x2000
	v_lshl_add_u64 v[232:233], s[26:27], 0, v[148:149]
	global_load_lds_dwordx4 v[232:233], off
	s_mov_b32 m0, s38
	v_lshl_add_u64 v[232:233], s[34:35], 0, v[146:147]
	global_load_lds_dwordx4 v[232:233], off
	s_mov_b32 m0, s39
	s_nop 0
	global_load_lds_dwordx4 v[234:235], off
	s_waitcnt vmcnt(8)
	s_waitcnt lgkmcnt(0)
	s_barrier
	s_setprio 1
	s_waitcnt lgkmcnt(0)
	v_mfma_f32_16x16x32_bf16 v[66:69], v[58:61], v[198:201], v[66:69]
	v_mfma_f32_16x16x32_bf16 v[62:65], v[114:117], v[198:201], v[62:65]
	v_mfma_f32_16x16x32_bf16 v[46:49], v[58:61], v[206:209], v[46:49]
	v_mfma_f32_16x16x32_bf16 v[42:45], v[114:117], v[206:209], v[42:45]
	v_mfma_f32_16x16x32_bf16 v[30:33], v[58:61], v[214:217], v[30:33]
	v_mfma_f32_16x16x32_bf16 v[26:29], v[114:117], v[214:217], v[26:29]
	v_mfma_f32_16x16x32_bf16 v[14:17], v[58:61], v[222:225], v[14:17]
	v_mfma_f32_16x16x32_bf16 v[10:13], v[114:117], v[222:225], v[10:13]
	v_mfma_f32_16x16x32_bf16 v[66:69], v[110:113], v[202:205], v[66:69]
	v_mfma_f32_16x16x32_bf16 v[62:65], v[122:125], v[202:205], v[62:65]
	v_mfma_f32_16x16x32_bf16 v[46:49], v[110:113], v[210:213], v[46:49]
	v_mfma_f32_16x16x32_bf16 v[42:45], v[122:125], v[210:213], v[42:45]
	v_mfma_f32_16x16x32_bf16 v[30:33], v[110:113], v[218:221], v[30:33]
	v_mfma_f32_16x16x32_bf16 v[26:29], v[122:125], v[218:221], v[26:29]
	v_mfma_f32_16x16x32_bf16 v[14:17], v[110:113], v[226:229], v[14:17]
	v_mfma_f32_16x16x32_bf16 v[10:13], v[122:125], v[226:229], v[10:13]
	s_setprio 0
	s_setprio 1
	v_mfma_f32_16x16x32_bf16 v[54:57], v[182:185], v[198:201], v[54:57]
	v_mfma_f32_16x16x32_bf16 v[50:53], v[190:193], v[198:201], v[50:53]
	v_mfma_f32_16x16x32_bf16 v[38:41], v[182:185], v[206:209], v[38:41]
	v_mfma_f32_16x16x32_bf16 v[34:37], v[190:193], v[206:209], v[34:37]
	v_mfma_f32_16x16x32_bf16 v[22:25], v[182:185], v[214:217], v[22:25]
	v_mfma_f32_16x16x32_bf16 v[18:21], v[190:193], v[214:217], v[18:21]
	v_mfma_f32_16x16x32_bf16 v[6:9], v[182:185], v[222:225], v[6:9]
	v_mfma_f32_16x16x32_bf16 v[2:5], v[190:193], v[222:225], v[2:5]
	v_mfma_f32_16x16x32_bf16 v[54:57], v[186:189], v[202:205], v[54:57]
	v_mfma_f32_16x16x32_bf16 v[50:53], v[194:197], v[202:205], v[50:53]
	v_mfma_f32_16x16x32_bf16 v[38:41], v[186:189], v[210:213], v[38:41]
	v_mfma_f32_16x16x32_bf16 v[34:37], v[194:197], v[210:213], v[34:37]
	v_mfma_f32_16x16x32_bf16 v[22:25], v[186:189], v[218:221], v[22:25]
	v_mfma_f32_16x16x32_bf16 v[18:21], v[194:197], v[218:221], v[18:21]
	v_mfma_f32_16x16x32_bf16 v[6:9], v[186:189], v[226:229], v[6:9]
	v_mfma_f32_16x16x32_bf16 v[2:5], v[194:197], v[226:229], v[2:5]
	s_setprio 0
	s_barrier
	s_add_i32 s55, 0, 0x18000
	s_add_i32 s56, 0, 0x1c000
	v_add_u32_e32 v122, s55, v176
	v_add_u32_e32 v181, s56, v176
	ds_read_b128 v[58:61], v122
	ds_read_b128 v[110:113], v122 offset:1024
	ds_read_b128 v[114:117], v122 offset:2048
	ds_read_b128 v[122:125], v122 offset:3072
	ds_read_b128 v[182:185], v181
	ds_read_b128 v[186:189], v181 offset:1024
	ds_read_b128 v[190:193], v181 offset:2048
	ds_read_b128 v[194:197], v181 offset:3072
	s_add_u32 s26, s34, 0x40000
	s_addc_u32 s27, s35, 0
	s_mov_b32 m0, s40
	v_lshl_add_u64 v[236:237], s[26:27], 0, v[146:147]
	ds_read_b128 v[198:201], v180 offset:32768
	ds_read_b128 v[202:205], v180 offset:33792
	ds_read_b128 v[206:209], v180 offset:34816
	ds_read_b128 v[210:213], v180 offset:35840
	ds_read_b128 v[214:217], v180 offset:36864
	ds_read_b128 v[218:221], v180 offset:37888
	ds_read_b128 v[222:225], v180 offset:38912
	ds_read_b128 v[226:229], v180 offset:39936
	global_load_lds_dwordx4 v[236:237], off
	s_mov_b32 m0, s41
	v_lshl_add_u64 v[236:237], s[26:27], 0, v[148:149]
	global_load_lds_dwordx4 v[236:237], off
	s_waitcnt vmcnt(8)
	s_waitcnt lgkmcnt(0)
	s_barrier
	s_setprio 1
	s_waitcnt lgkmcnt(0)
	v_mfma_f32_16x16x32_bf16 v[142:145], v[58:61], v[198:201], v[142:145]
	v_mfma_f32_16x16x32_bf16 v[138:141], v[114:117], v[198:201], v[138:141]
	v_mfma_f32_16x16x32_bf16 v[130:133], v[58:61], v[206:209], v[130:133]
	v_mfma_f32_16x16x32_bf16 v[118:121], v[114:117], v[206:209], v[118:121]
	v_mfma_f32_16x16x32_bf16 v[102:105], v[58:61], v[214:217], v[102:105]
	v_mfma_f32_16x16x32_bf16 v[94:97], v[114:117], v[214:217], v[94:97]
	v_mfma_f32_16x16x32_bf16 v[86:89], v[58:61], v[222:225], v[86:89]
	v_mfma_f32_16x16x32_bf16 v[78:81], v[114:117], v[222:225], v[78:81]
	v_mfma_f32_16x16x32_bf16 v[142:145], v[110:113], v[202:205], v[142:145]
	v_mfma_f32_16x16x32_bf16 v[138:141], v[122:125], v[202:205], v[138:141]
	v_mfma_f32_16x16x32_bf16 v[130:133], v[110:113], v[210:213], v[130:133]
	v_mfma_f32_16x16x32_bf16 v[118:121], v[122:125], v[210:213], v[118:121]
	v_mfma_f32_16x16x32_bf16 v[102:105], v[110:113], v[218:221], v[102:105]
	v_mfma_f32_16x16x32_bf16 v[94:97], v[122:125], v[218:221], v[94:97]
	v_mfma_f32_16x16x32_bf16 v[86:89], v[110:113], v[226:229], v[86:89]
	v_mfma_f32_16x16x32_bf16 v[78:81], v[122:125], v[226:229], v[78:81]
	s_setprio 0
	s_setprio 1
	v_mfma_f32_16x16x32_bf16 v[134:137], v[182:185], v[198:201], v[134:137]
	v_mfma_f32_16x16x32_bf16 v[126:129], v[190:193], v[198:201], v[126:129]
	v_mfma_f32_16x16x32_bf16 v[106:109], v[182:185], v[206:209], v[106:109]
	v_mfma_f32_16x16x32_bf16 v[98:101], v[190:193], v[206:209], v[98:101]
	v_mfma_f32_16x16x32_bf16 v[90:93], v[182:185], v[214:217], v[90:93]
	v_mfma_f32_16x16x32_bf16 v[82:85], v[190:193], v[214:217], v[82:85]
	v_mfma_f32_16x16x32_bf16 v[74:77], v[182:185], v[222:225], v[74:77]
	v_mfma_f32_16x16x32_bf16 v[70:73], v[190:193], v[222:225], v[70:73]
	v_mfma_f32_16x16x32_bf16 v[134:137], v[186:189], v[202:205], v[134:137]
	v_mfma_f32_16x16x32_bf16 v[126:129], v[194:197], v[202:205], v[126:129]
	v_mfma_f32_16x16x32_bf16 v[106:109], v[186:189], v[210:213], v[106:109]
	v_mfma_f32_16x16x32_bf16 v[98:101], v[194:197], v[210:213], v[98:101]
	v_mfma_f32_16x16x32_bf16 v[90:93], v[186:189], v[218:221], v[90:93]
	v_mfma_f32_16x16x32_bf16 v[82:85], v[194:197], v[218:221], v[82:85]
	v_mfma_f32_16x16x32_bf16 v[74:77], v[186:189], v[226:229], v[74:77]
	v_mfma_f32_16x16x32_bf16 v[70:73], v[194:197], v[226:229], v[70:73]
	s_setprio 0
	s_barrier
	s_add_i32 s26, s55, s37
	v_lshl_add_u64 v[174:175], v[174:175], 0, s[12:13]
	s_mov_b32 m0, s26
	ds_read_b128 v[198:201], v180 offset:49152
	ds_read_b128 v[202:205], v180 offset:50176
	ds_read_b128 v[206:209], v180 offset:51200
	ds_read_b128 v[210:213], v180 offset:52224
	ds_read_b128 v[214:217], v180 offset:53248
	ds_read_b128 v[218:221], v180 offset:54272
	ds_read_b128 v[222:225], v180 offset:55296
	ds_read_b128 v[226:229], v180 offset:56320
	global_load_lds_dwordx4 v[174:175], off
	s_add_i32 m0, s26, 0x2000
	s_add_u32 s26, s30, 0x40080
	v_lshl_add_u64 v[174:175], v[230:231], 0, s[12:13]
	s_addc_u32 s27, s31, 0
	s_add_i32 s30, s56, s37
	global_load_lds_dwordx4 v[174:175], off
	s_mov_b32 m0, s30
	v_lshl_add_u64 v[174:175], s[26:27], 0, v[146:147]
	global_load_lds_dwordx4 v[174:175], off
	s_add_i32 m0, s30, 0x2000
	v_lshl_add_u64 v[174:175], s[26:27], 0, v[148:149]
	global_load_lds_dwordx4 v[174:175], off
	s_mov_b32 m0, s45
	v_lshl_add_u64 v[174:175], v[232:233], 0, s[12:13]
	global_load_lds_dwordx4 v[174:175], off
	s_mov_b32 m0, s46
	v_lshl_add_u64 v[174:175], v[234:235], 0, s[12:13]
	global_load_lds_dwordx4 v[174:175], off
	s_waitcnt vmcnt(8)
	s_waitcnt lgkmcnt(0)
	s_barrier
	s_setprio 1
	s_waitcnt lgkmcnt(0)
	v_mfma_f32_16x16x32_bf16 v[66:69], v[58:61], v[198:201], v[66:69]
	v_mfma_f32_16x16x32_bf16 v[62:65], v[114:117], v[198:201], v[62:65]
	v_mfma_f32_16x16x32_bf16 v[46:49], v[58:61], v[206:209], v[46:49]
	v_mfma_f32_16x16x32_bf16 v[42:45], v[114:117], v[206:209], v[42:45]
	v_mfma_f32_16x16x32_bf16 v[30:33], v[58:61], v[214:217], v[30:33]
	v_mfma_f32_16x16x32_bf16 v[26:29], v[114:117], v[214:217], v[26:29]
	v_mfma_f32_16x16x32_bf16 v[14:17], v[58:61], v[222:225], v[14:17]
	v_mfma_f32_16x16x32_bf16 v[10:13], v[114:117], v[222:225], v[10:13]
	v_mfma_f32_16x16x32_bf16 v[66:69], v[110:113], v[202:205], v[66:69]
	v_mfma_f32_16x16x32_bf16 v[62:65], v[122:125], v[202:205], v[62:65]
	v_mfma_f32_16x16x32_bf16 v[46:49], v[110:113], v[210:213], v[46:49]
	v_mfma_f32_16x16x32_bf16 v[42:45], v[122:125], v[210:213], v[42:45]
	v_mfma_f32_16x16x32_bf16 v[30:33], v[110:113], v[218:221], v[30:33]
	v_mfma_f32_16x16x32_bf16 v[26:29], v[122:125], v[218:221], v[26:29]
	v_mfma_f32_16x16x32_bf16 v[14:17], v[110:113], v[226:229], v[14:17]
	v_mfma_f32_16x16x32_bf16 v[10:13], v[122:125], v[226:229], v[10:13]
	s_setprio 0
	s_setprio 1
	v_mfma_f32_16x16x32_bf16 v[54:57], v[182:185], v[198:201], v[54:57]
	v_mfma_f32_16x16x32_bf16 v[50:53], v[190:193], v[198:201], v[50:53]
	v_mfma_f32_16x16x32_bf16 v[38:41], v[182:185], v[206:209], v[38:41]
	v_mfma_f32_16x16x32_bf16 v[34:37], v[190:193], v[206:209], v[34:37]
	v_mfma_f32_16x16x32_bf16 v[22:25], v[182:185], v[214:217], v[22:25]
	v_mfma_f32_16x16x32_bf16 v[18:21], v[190:193], v[214:217], v[18:21]
	v_mfma_f32_16x16x32_bf16 v[6:9], v[182:185], v[222:225], v[6:9]
	v_mfma_f32_16x16x32_bf16 v[2:5], v[190:193], v[222:225], v[2:5]
	v_mfma_f32_16x16x32_bf16 v[54:57], v[186:189], v[202:205], v[54:57]
	v_mfma_f32_16x16x32_bf16 v[50:53], v[194:197], v[202:205], v[50:53]
	v_mfma_f32_16x16x32_bf16 v[38:41], v[186:189], v[210:213], v[38:41]
	v_mfma_f32_16x16x32_bf16 v[34:37], v[194:197], v[210:213], v[34:37]
	v_mfma_f32_16x16x32_bf16 v[22:25], v[186:189], v[218:221], v[22:25]
	v_mfma_f32_16x16x32_bf16 v[18:21], v[194:197], v[218:221], v[18:21]
	v_mfma_f32_16x16x32_bf16 v[6:9], v[186:189], v[226:229], v[6:9]
	v_mfma_f32_16x16x32_bf16 v[2:5], v[194:197], v[226:229], v[2:5]
	s_setprio 0
	s_barrier
	s_add_i32 s54, s54, 2
	s_add_u32 s52, s52, 0x100
	s_addc_u32 s53, s53, 0
	s_cmp_gt_u32 s54, 13
	s_mov_b64 s[26:27], s[28:29]
	s_cbranch_scc0 .LBB0_1101
	s_and_b64 vcc, exec, s[14:15]
	s_cbranch_vccz .LBB0_1104
	s_barrier

.LBB0_1367:
	ds_read_b128 v[158:161], v178
	ds_read_b128 v[162:165], v178 offset:1024
	ds_read_b128 v[166:169], v178 offset:2048
	ds_read_b128 v[170:173], v178 offset:3072
	ds_read_b128 v[182:185], v179
	ds_read_b128 v[186:189], v179 offset:1024
	ds_read_b128 v[190:193], v179 offset:2048
	ds_read_b128 v[194:197], v179 offset:3072
	s_add_u32 s22, s20, 0x100
	s_addc_u32 s23, s21, 0
	s_cmp_eq_u32 s50, 40
	s_cselect_b32 s27, s7, s23
	s_cselect_b32 s26, s6, s22
	s_cselect_b32 s25, s19, s49
	s_cselect_b32 s24, s18, s2
	v_lshl_add_u64 v[174:175], s[20:21], 0, v[150:151]
	s_add_i32 m0, s31, 0xc000
	ds_read_b128 v[198:201], v180
	ds_read_b128 v[202:205], v180 offset:1024
	ds_read_b128 v[206:209], v180 offset:2048
	ds_read_b128 v[210:213], v180 offset:3072
	ds_read_b128 v[214:217], v180 offset:4096
	ds_read_b128 v[218:221], v180 offset:5120
	ds_read_b128 v[222:225], v180 offset:6144
	ds_read_b128 v[226:229], v180 offset:7168
	global_load_lds_dwordx4 v[174:175], off
	s_add_i32 m0, s31, 0xe000
	v_lshl_add_u64 v[174:175], s[20:21], 0, v[152:153]
	global_load_lds_dwordx4 v[174:175], off
	s_waitcnt vmcnt(8)
	s_waitcnt lgkmcnt(0)
	s_barrier
	s_setprio 1
	s_waitcnt lgkmcnt(0)
	v_mfma_f32_16x16x32_bf16 v[126:129], v[158:161], v[198:201], v[126:129]
	v_mfma_f32_16x16x32_bf16 v[122:125], v[166:169], v[198:201], v[122:125]
	v_mfma_f32_16x16x32_bf16 v[114:117], v[158:161], v[206:209], v[114:117]
	v_mfma_f32_16x16x32_bf16 v[106:109], v[166:169], v[206:209], v[106:109]
	v_mfma_f32_16x16x32_bf16 v[98:101], v[158:161], v[214:217], v[98:101]
	v_mfma_f32_16x16x32_bf16 v[90:93], v[166:169], v[214:217], v[90:93]
	v_mfma_f32_16x16x32_bf16 v[78:81], v[158:161], v[222:225], v[78:81]
	v_mfma_f32_16x16x32_bf16 v[74:77], v[166:169], v[222:225], v[74:77]
	v_mfma_f32_16x16x32_bf16 v[126:129], v[162:165], v[202:205], v[126:129]
	v_mfma_f32_16x16x32_bf16 v[122:125], v[170:173], v[202:205], v[122:125]
	v_mfma_f32_16x16x32_bf16 v[114:117], v[162:165], v[210:213], v[114:117]
	v_mfma_f32_16x16x32_bf16 v[106:109], v[170:173], v[210:213], v[106:109]
	v_mfma_f32_16x16x32_bf16 v[98:101], v[162:165], v[218:221], v[98:101]
	v_mfma_f32_16x16x32_bf16 v[90:93], v[170:173], v[218:221], v[90:93]
	v_mfma_f32_16x16x32_bf16 v[78:81], v[162:165], v[226:229], v[78:81]
	v_mfma_f32_16x16x32_bf16 v[74:77], v[170:173], v[226:229], v[74:77]
	s_setprio 0
	s_setprio 1
	v_mfma_f32_16x16x32_bf16 v[118:121], v[182:185], v[198:201], v[118:121]
	v_mfma_f32_16x16x32_bf16 v[110:113], v[190:193], v[198:201], v[110:113]
	v_mfma_f32_16x16x32_bf16 v[102:105], v[182:185], v[206:209], v[102:105]
	v_mfma_f32_16x16x32_bf16 v[94:97], v[190:193], v[206:209], v[94:97]
	v_mfma_f32_16x16x32_bf16 v[86:89], v[182:185], v[214:217], v[86:89]
	v_mfma_f32_16x16x32_bf16 v[82:85], v[190:193], v[214:217], v[82:85]
	v_mfma_f32_16x16x32_bf16 v[70:73], v[182:185], v[222:225], v[70:73]
	v_mfma_f32_16x16x32_bf16 v[66:69], v[190:193], v[222:225], v[66:69]
	v_mfma_f32_16x16x32_bf16 v[118:121], v[186:189], v[202:205], v[118:121]
	v_mfma_f32_16x16x32_bf16 v[110:113], v[194:197], v[202:205], v[110:113]
	v_mfma_f32_16x16x32_bf16 v[102:105], v[186:189], v[210:213], v[102:105]
	v_mfma_f32_16x16x32_bf16 v[94:97], v[194:197], v[210:213], v[94:97]
	v_mfma_f32_16x16x32_bf16 v[86:89], v[186:189], v[218:221], v[86:89]
	v_mfma_f32_16x16x32_bf16 v[82:85], v[194:197], v[218:221], v[82:85]
	v_mfma_f32_16x16x32_bf16 v[70:73], v[186:189], v[226:229], v[70:73]
	v_mfma_f32_16x16x32_bf16 v[66:69], v[194:197], v[226:229], v[66:69]
	s_setprio 0
	s_barrier
	s_add_i32 s20, s43, s30
	v_lshl_add_u64 v[174:175], s[24:25], 0, v[130:131]
	s_mov_b32 m0, s20
	ds_read_b128 v[198:201], v180 offset:16384
	ds_read_b128 v[202:205], v180 offset:17408
	ds_read_b128 v[206:209], v180 offset:18432
	ds_read_b128 v[210:213], v180 offset:19456
	ds_read_b128 v[214:217], v180 offset:20480
	ds_read_b128 v[218:221], v180 offset:21504
	ds_read_b128 v[222:225], v180 offset:22528
	ds_read_b128 v[226:229], v180 offset:23552
	global_load_lds_dwordx4 v[174:175], off
	s_add_i32 m0, s20, 0x2000
	s_add_u32 s20, s24, 0xb0000
	v_lshl_add_u64 v[230:231], s[24:25], 0, v[132:133]
	s_addc_u32 s21, s25, 0
	s_add_i32 s51, s44, s30
	global_load_lds_dwordx4 v[230:231], off
	v_lshl_add_u64 v[232:233], s[20:21], 0, v[130:131]
	s_mov_b32 m0, s51
	v_lshl_add_u64 v[234:235], s[26:27], 0, v[132:133]
	global_load_lds_dwordx4 v[232:233], off
	s_add_i32 m0, s51, 0x2000
	v_lshl_add_u64 v[232:233], s[20:21], 0, v[132:133]
	global_load_lds_dwordx4 v[232:233], off
	s_mov_b32 m0, s31
	v_lshl_add_u64 v[232:233], s[26:27], 0, v[130:131]
	global_load_lds_dwordx4 v[232:233], off
	s_mov_b32 m0, s33
	s_nop 0
	global_load_lds_dwordx4 v[234:235], off
	s_waitcnt vmcnt(8)
	s_waitcnt lgkmcnt(0)
	s_barrier
	s_setprio 1
	s_waitcnt lgkmcnt(0)
	v_mfma_f32_16x16x32_bf16 v[62:65], v[158:161], v[198:201], v[62:65]
	v_mfma_f32_16x16x32_bf16 v[58:61], v[166:169], v[198:201], v[58:61]
	v_mfma_f32_16x16x32_bf16 v[46:49], v[158:161], v[206:209], v[46:49]
	v_mfma_f32_16x16x32_bf16 v[42:45], v[166:169], v[206:209], v[42:45]
	v_mfma_f32_16x16x32_bf16 v[30:33], v[158:161], v[214:217], v[30:33]
	v_mfma_f32_16x16x32_bf16 v[26:29], v[166:169], v[214:217], v[26:29]
	v_mfma_f32_16x16x32_bf16 v[14:17], v[158:161], v[222:225], v[14:17]
	v_mfma_f32_16x16x32_bf16 v[10:13], v[166:169], v[222:225], v[10:13]
	v_mfma_f32_16x16x32_bf16 v[62:65], v[162:165], v[202:205], v[62:65]
	v_mfma_f32_16x16x32_bf16 v[58:61], v[170:173], v[202:205], v[58:61]
	v_mfma_f32_16x16x32_bf16 v[46:49], v[162:165], v[210:213], v[46:49]
	v_mfma_f32_16x16x32_bf16 v[42:45], v[170:173], v[210:213], v[42:45]
	v_mfma_f32_16x16x32_bf16 v[30:33], v[162:165], v[218:221], v[30:33]
	v_mfma_f32_16x16x32_bf16 v[26:29], v[170:173], v[218:221], v[26:29]
	v_mfma_f32_16x16x32_bf16 v[14:17], v[162:165], v[226:229], v[14:17]
	v_mfma_f32_16x16x32_bf16 v[10:13], v[170:173], v[226:229], v[10:13]
	s_setprio 0
	s_setprio 1
	v_mfma_f32_16x16x32_bf16 v[54:57], v[182:185], v[198:201], v[54:57]
	v_mfma_f32_16x16x32_bf16 v[50:53], v[190:193], v[198:201], v[50:53]
	v_mfma_f32_16x16x32_bf16 v[38:41], v[182:185], v[206:209], v[38:41]
	v_mfma_f32_16x16x32_bf16 v[34:37], v[190:193], v[206:209], v[34:37]
	v_mfma_f32_16x16x32_bf16 v[22:25], v[182:185], v[214:217], v[22:25]
	v_mfma_f32_16x16x32_bf16 v[18:21], v[190:193], v[214:217], v[18:21]
	v_mfma_f32_16x16x32_bf16 v[6:9], v[182:185], v[222:225], v[6:9]
	v_mfma_f32_16x16x32_bf16 v[2:5], v[190:193], v[222:225], v[2:5]
	v_mfma_f32_16x16x32_bf16 v[54:57], v[186:189], v[202:205], v[54:57]
	v_mfma_f32_16x16x32_bf16 v[50:53], v[194:197], v[202:205], v[50:53]
	v_mfma_f32_16x16x32_bf16 v[38:41], v[186:189], v[210:213], v[38:41]
	v_mfma_f32_16x16x32_bf16 v[34:37], v[194:197], v[210:213], v[34:37]
	v_mfma_f32_16x16x32_bf16 v[22:25], v[186:189], v[218:221], v[22:25]
	v_mfma_f32_16x16x32_bf16 v[18:21], v[194:197], v[218:221], v[18:21]
	v_mfma_f32_16x16x32_bf16 v[6:9], v[186:189], v[226:229], v[6:9]
	v_mfma_f32_16x16x32_bf16 v[2:5], v[194:197], v[226:229], v[2:5]
	s_setprio 0
	s_barrier
	s_add_i32 s51, 0, 0x18000
	s_add_i32 s52, 0, 0x1c000
	v_add_u32_e32 v170, s51, v176
	v_add_u32_e32 v181, s52, v176
	ds_read_b128 v[158:161], v170
	ds_read_b128 v[162:165], v170 offset:1024
	ds_read_b128 v[166:169], v170 offset:2048
	ds_read_b128 v[170:173], v170 offset:3072
	ds_read_b128 v[182:185], v181
	ds_read_b128 v[186:189], v181 offset:1024
	ds_read_b128 v[190:193], v181 offset:2048
	ds_read_b128 v[194:197], v181 offset:3072
	s_add_u32 s20, s26, 0xb0000
	s_addc_u32 s21, s27, 0
	s_mov_b32 m0, s34
	v_lshl_add_u64 v[236:237], s[20:21], 0, v[130:131]
	ds_read_b128 v[198:201], v180 offset:32768
	ds_read_b128 v[202:205], v180 offset:33792
	ds_read_b128 v[206:209], v180 offset:34816
	ds_read_b128 v[210:213], v180 offset:35840
	ds_read_b128 v[214:217], v180 offset:36864
	ds_read_b128 v[218:221], v180 offset:37888
	ds_read_b128 v[222:225], v180 offset:38912
	ds_read_b128 v[226:229], v180 offset:39936
	global_load_lds_dwordx4 v[236:237], off
	s_mov_b32 m0, s35
	v_lshl_add_u64 v[236:237], s[20:21], 0, v[132:133]
	global_load_lds_dwordx4 v[236:237], off
	s_waitcnt vmcnt(8)
	s_waitcnt lgkmcnt(0)
	s_barrier
	s_setprio 1
	s_waitcnt lgkmcnt(0)
	v_mfma_f32_16x16x32_bf16 v[126:129], v[158:161], v[198:201], v[126:129]
	v_mfma_f32_16x16x32_bf16 v[122:125], v[166:169], v[198:201], v[122:125]
	v_mfma_f32_16x16x32_bf16 v[114:117], v[158:161], v[206:209], v[114:117]
	v_mfma_f32_16x16x32_bf16 v[106:109], v[166:169], v[206:209], v[106:109]
	v_mfma_f32_16x16x32_bf16 v[98:101], v[158:161], v[214:217], v[98:101]
	v_mfma_f32_16x16x32_bf16 v[90:93], v[166:169], v[214:217], v[90:93]
	v_mfma_f32_16x16x32_bf16 v[78:81], v[158:161], v[222:225], v[78:81]
	v_mfma_f32_16x16x32_bf16 v[74:77], v[166:169], v[222:225], v[74:77]
	v_mfma_f32_16x16x32_bf16 v[126:129], v[162:165], v[202:205], v[126:129]
	v_mfma_f32_16x16x32_bf16 v[122:125], v[170:173], v[202:205], v[122:125]
	v_mfma_f32_16x16x32_bf16 v[114:117], v[162:165], v[210:213], v[114:117]
	v_mfma_f32_16x16x32_bf16 v[106:109], v[170:173], v[210:213], v[106:109]
	v_mfma_f32_16x16x32_bf16 v[98:101], v[162:165], v[218:221], v[98:101]
	v_mfma_f32_16x16x32_bf16 v[90:93], v[170:173], v[218:221], v[90:93]
	v_mfma_f32_16x16x32_bf16 v[78:81], v[162:165], v[226:229], v[78:81]
	v_mfma_f32_16x16x32_bf16 v[74:77], v[170:173], v[226:229], v[74:77]
	s_setprio 0
	s_setprio 1
	v_mfma_f32_16x16x32_bf16 v[118:121], v[182:185], v[198:201], v[118:121]
	v_mfma_f32_16x16x32_bf16 v[110:113], v[190:193], v[198:201], v[110:113]
	v_mfma_f32_16x16x32_bf16 v[102:105], v[182:185], v[206:209], v[102:105]
	v_mfma_f32_16x16x32_bf16 v[94:97], v[190:193], v[206:209], v[94:97]
	v_mfma_f32_16x16x32_bf16 v[86:89], v[182:185], v[214:217], v[86:89]
	v_mfma_f32_16x16x32_bf16 v[82:85], v[190:193], v[214:217], v[82:85]
	v_mfma_f32_16x16x32_bf16 v[70:73], v[182:185], v[222:225], v[70:73]
	v_mfma_f32_16x16x32_bf16 v[66:69], v[190:193], v[222:225], v[66:69]
	v_mfma_f32_16x16x32_bf16 v[118:121], v[186:189], v[202:205], v[118:121]
	v_mfma_f32_16x16x32_bf16 v[110:113], v[194:197], v[202:205], v[110:113]
	v_mfma_f32_16x16x32_bf16 v[102:105], v[186:189], v[210:213], v[102:105]
	v_mfma_f32_16x16x32_bf16 v[94:97], v[194:197], v[210:213], v[94:97]
	v_mfma_f32_16x16x32_bf16 v[86:89], v[186:189], v[218:221], v[86:89]
	v_mfma_f32_16x16x32_bf16 v[82:85], v[194:197], v[218:221], v[82:85]
	v_mfma_f32_16x16x32_bf16 v[70:73], v[186:189], v[226:229], v[70:73]
	v_mfma_f32_16x16x32_bf16 v[66:69], v[194:197], v[226:229], v[66:69]
	s_setprio 0
	s_barrier
	s_add_i32 s20, s51, s30
	v_lshl_add_u64 v[174:175], v[174:175], 0, s[14:15]
	s_mov_b32 m0, s20
	ds_read_b128 v[198:201], v180 offset:49152
	ds_read_b128 v[202:205], v180 offset:50176
	ds_read_b128 v[206:209], v180 offset:51200
	ds_read_b128 v[210:213], v180 offset:52224
	ds_read_b128 v[214:217], v180 offset:53248
	ds_read_b128 v[218:221], v180 offset:54272
	ds_read_b128 v[222:225], v180 offset:55296
	ds_read_b128 v[226:229], v180 offset:56320
	global_load_lds_dwordx4 v[174:175], off
	s_add_i32 m0, s20, 0x2000
	s_add_u32 s20, s24, 0xb0080
	v_lshl_add_u64 v[174:175], v[230:231], 0, s[14:15]
	s_addc_u32 s21, s25, 0
	s_add_i32 s24, s52, s30
	global_load_lds_dwordx4 v[174:175], off
	s_mov_b32 m0, s24
	v_lshl_add_u64 v[174:175], s[20:21], 0, v[130:131]
	global_load_lds_dwordx4 v[174:175], off
	s_add_i32 m0, s24, 0x2000
	v_lshl_add_u64 v[174:175], s[20:21], 0, v[132:133]
	global_load_lds_dwordx4 v[174:175], off
	s_mov_b32 m0, s39
	v_lshl_add_u64 v[174:175], v[232:233], 0, s[14:15]
	global_load_lds_dwordx4 v[174:175], off
	s_mov_b32 m0, s40
	v_lshl_add_u64 v[174:175], v[234:235], 0, s[14:15]
	global_load_lds_dwordx4 v[174:175], off
	s_waitcnt vmcnt(8)
	s_waitcnt lgkmcnt(0)
	s_barrier
	s_setprio 1
	s_waitcnt lgkmcnt(0)
	v_mfma_f32_16x16x32_bf16 v[62:65], v[158:161], v[198:201], v[62:65]
	v_mfma_f32_16x16x32_bf16 v[58:61], v[166:169], v[198:201], v[58:61]
	v_mfma_f32_16x16x32_bf16 v[46:49], v[158:161], v[206:209], v[46:49]
	v_mfma_f32_16x16x32_bf16 v[42:45], v[166:169], v[206:209], v[42:45]
	v_mfma_f32_16x16x32_bf16 v[30:33], v[158:161], v[214:217], v[30:33]
	v_mfma_f32_16x16x32_bf16 v[26:29], v[166:169], v[214:217], v[26:29]
	v_mfma_f32_16x16x32_bf16 v[14:17], v[158:161], v[222:225], v[14:17]
	v_mfma_f32_16x16x32_bf16 v[10:13], v[166:169], v[222:225], v[10:13]
	v_mfma_f32_16x16x32_bf16 v[62:65], v[162:165], v[202:205], v[62:65]
	v_mfma_f32_16x16x32_bf16 v[58:61], v[170:173], v[202:205], v[58:61]
	v_mfma_f32_16x16x32_bf16 v[46:49], v[162:165], v[210:213], v[46:49]
	v_mfma_f32_16x16x32_bf16 v[42:45], v[170:173], v[210:213], v[42:45]
	v_mfma_f32_16x16x32_bf16 v[30:33], v[162:165], v[218:221], v[30:33]
	v_mfma_f32_16x16x32_bf16 v[26:29], v[170:173], v[218:221], v[26:29]
	v_mfma_f32_16x16x32_bf16 v[14:17], v[162:165], v[226:229], v[14:17]
	v_mfma_f32_16x16x32_bf16 v[10:13], v[170:173], v[226:229], v[10:13]
	s_setprio 0
	s_setprio 1
	v_mfma_f32_16x16x32_bf16 v[54:57], v[182:185], v[198:201], v[54:57]
	v_mfma_f32_16x16x32_bf16 v[50:53], v[190:193], v[198:201], v[50:53]
	v_mfma_f32_16x16x32_bf16 v[38:41], v[182:185], v[206:209], v[38:41]
	v_mfma_f32_16x16x32_bf16 v[34:37], v[190:193], v[206:209], v[34:37]
	v_mfma_f32_16x16x32_bf16 v[22:25], v[182:185], v[214:217], v[22:25]
	v_mfma_f32_16x16x32_bf16 v[18:21], v[190:193], v[214:217], v[18:21]
	v_mfma_f32_16x16x32_bf16 v[6:9], v[182:185], v[222:225], v[6:9]
	v_mfma_f32_16x16x32_bf16 v[2:5], v[190:193], v[222:225], v[2:5]
	v_mfma_f32_16x16x32_bf16 v[54:57], v[186:189], v[202:205], v[54:57]
	v_mfma_f32_16x16x32_bf16 v[50:53], v[194:197], v[202:205], v[50:53]
	v_mfma_f32_16x16x32_bf16 v[38:41], v[186:189], v[210:213], v[38:41]
	v_mfma_f32_16x16x32_bf16 v[34:37], v[194:197], v[210:213], v[34:37]
	v_mfma_f32_16x16x32_bf16 v[22:25], v[186:189], v[218:221], v[22:25]
	v_mfma_f32_16x16x32_bf16 v[18:21], v[194:197], v[218:221], v[18:21]
	v_mfma_f32_16x16x32_bf16 v[6:9], v[186:189], v[226:229], v[6:9]
	v_mfma_f32_16x16x32_bf16 v[2:5], v[194:197], v[226:229], v[2:5]
	s_setprio 0
	s_barrier
	s_add_i32 s50, s50, 2
	s_add_u32 s2, s2, 0x100
	s_addc_u32 s49, s49, 0
	s_cmp_gt_u32 s50, 41
	s_mov_b64 s[20:21], s[22:23]
	s_cbranch_scc0 .LBB0_1367
	s_and_b64 vcc, exec, s[16:17]
	s_cbranch_vccz .LBB0_1370
	s_barrier

.LBB0_2328:
	ds_read_b128 v[86:89], v178
	ds_read_b128 v[126:129], v178 offset:1024
	ds_read_b128 v[130:133], v178 offset:2048
	ds_read_b128 v[138:141], v178 offset:3072
	ds_read_b128 v[182:185], v179
	ds_read_b128 v[186:189], v179 offset:1024
	ds_read_b128 v[190:193], v179 offset:2048
	ds_read_b128 v[194:197], v179 offset:3072
	s_add_u32 s24, s22, 0x100
	s_addc_u32 s25, s23, 0
	s_cmp_eq_u32 s55, 12
	s_cselect_b32 s29, s2, s25
	s_cselect_b32 s28, s15, s24
	s_cselect_b32 s27, s13, s54
	s_cselect_b32 s26, s52, s53
	v_lshl_add_u64 v[174:175], s[22:23], 0, v[166:167]
	s_add_i32 m0, s36, 0xc000
	ds_read_b128 v[198:201], v180
	ds_read_b128 v[202:205], v180 offset:1024
	ds_read_b128 v[206:209], v180 offset:2048
	ds_read_b128 v[210:213], v180 offset:3072
	ds_read_b128 v[214:217], v180 offset:4096
	ds_read_b128 v[218:221], v180 offset:5120
	ds_read_b128 v[222:225], v180 offset:6144
	ds_read_b128 v[226:229], v180 offset:7168
	global_load_lds_dwordx4 v[174:175], off
	s_add_i32 m0, s36, 0xe000
	v_lshl_add_u64 v[174:175], s[22:23], 0, v[168:169]
	global_load_lds_dwordx4 v[174:175], off
	s_waitcnt vmcnt(8)
	s_waitcnt lgkmcnt(0)
	s_barrier
	s_setprio 1
	s_waitcnt lgkmcnt(0)
	v_mfma_f32_16x16x32_bf16 v[142:145], v[86:89], v[198:201], v[142:145]
	v_mfma_f32_16x16x32_bf16 v[134:137], v[130:133], v[198:201], v[134:137]
	v_mfma_f32_16x16x32_bf16 v[118:121], v[86:89], v[206:209], v[118:121]
	v_mfma_f32_16x16x32_bf16 v[110:113], v[130:133], v[206:209], v[110:113]
	v_mfma_f32_16x16x32_bf16 v[102:105], v[86:89], v[214:217], v[102:105]
	v_mfma_f32_16x16x32_bf16 v[94:97], v[130:133], v[214:217], v[94:97]
	v_mfma_f32_16x16x32_bf16 v[82:85], v[86:89], v[222:225], v[82:85]
	v_mfma_f32_16x16x32_bf16 v[74:77], v[130:133], v[222:225], v[74:77]
	v_mfma_f32_16x16x32_bf16 v[142:145], v[126:129], v[202:205], v[142:145]
	v_mfma_f32_16x16x32_bf16 v[134:137], v[138:141], v[202:205], v[134:137]
	v_mfma_f32_16x16x32_bf16 v[118:121], v[126:129], v[210:213], v[118:121]
	v_mfma_f32_16x16x32_bf16 v[110:113], v[138:141], v[210:213], v[110:113]
	v_mfma_f32_16x16x32_bf16 v[102:105], v[126:129], v[218:221], v[102:105]
	v_mfma_f32_16x16x32_bf16 v[94:97], v[138:141], v[218:221], v[94:97]
	v_mfma_f32_16x16x32_bf16 v[82:85], v[126:129], v[226:229], v[82:85]
	v_mfma_f32_16x16x32_bf16 v[74:77], v[138:141], v[226:229], v[74:77]
	s_setprio 0
	s_setprio 1
	v_mfma_f32_16x16x32_bf16 v[122:125], v[182:185], v[198:201], v[122:125]
	v_mfma_f32_16x16x32_bf16 v[114:117], v[190:193], v[198:201], v[114:117]
	v_mfma_f32_16x16x32_bf16 v[106:109], v[182:185], v[206:209], v[106:109]
	v_mfma_f32_16x16x32_bf16 v[98:101], v[190:193], v[206:209], v[98:101]
	v_mfma_f32_16x16x32_bf16 v[90:93], v[182:185], v[214:217], v[90:93]
	v_mfma_f32_16x16x32_bf16 v[78:81], v[190:193], v[214:217], v[78:81]
	v_mfma_f32_16x16x32_bf16 v[70:73], v[182:185], v[222:225], v[70:73]
	v_mfma_f32_16x16x32_bf16 v[66:69], v[190:193], v[222:225], v[66:69]
	v_mfma_f32_16x16x32_bf16 v[122:125], v[186:189], v[202:205], v[122:125]
	v_mfma_f32_16x16x32_bf16 v[114:117], v[194:197], v[202:205], v[114:117]
	v_mfma_f32_16x16x32_bf16 v[106:109], v[186:189], v[210:213], v[106:109]
	v_mfma_f32_16x16x32_bf16 v[98:101], v[194:197], v[210:213], v[98:101]
	v_mfma_f32_16x16x32_bf16 v[90:93], v[186:189], v[218:221], v[90:93]
	v_mfma_f32_16x16x32_bf16 v[78:81], v[194:197], v[218:221], v[78:81]
	v_mfma_f32_16x16x32_bf16 v[70:73], v[186:189], v[226:229], v[70:73]
	v_mfma_f32_16x16x32_bf16 v[66:69], v[194:197], v[226:229], v[66:69]
	s_setprio 0
	s_barrier
	s_add_i32 s22, s49, s35
	v_lshl_add_u64 v[174:175], s[26:27], 0, v[146:147]
	s_mov_b32 m0, s22
	ds_read_b128 v[198:201], v180 offset:16384
	ds_read_b128 v[202:205], v180 offset:17408
	ds_read_b128 v[206:209], v180 offset:18432
	ds_read_b128 v[210:213], v180 offset:19456
	ds_read_b128 v[214:217], v180 offset:20480
	ds_read_b128 v[218:221], v180 offset:21504
	ds_read_b128 v[222:225], v180 offset:22528
	ds_read_b128 v[226:229], v180 offset:23552
	global_load_lds_dwordx4 v[174:175], off
	s_add_i32 m0, s22, 0x2000
	s_add_u32 s22, s26, 0x40000
	v_lshl_add_u64 v[230:231], s[26:27], 0, v[148:149]
	s_addc_u32 s23, s27, 0
	s_add_i32 s56, s50, s35
	global_load_lds_dwordx4 v[230:231], off
	v_lshl_add_u64 v[232:233], s[22:23], 0, v[146:147]
	s_mov_b32 m0, s56
	v_lshl_add_u64 v[234:235], s[28:29], 0, v[148:149]
	global_load_lds_dwordx4 v[232:233], off
	s_add_i32 m0, s56, 0x2000
	v_lshl_add_u64 v[232:233], s[22:23], 0, v[148:149]
	global_load_lds_dwordx4 v[232:233], off
	s_mov_b32 m0, s36
	v_lshl_add_u64 v[232:233], s[28:29], 0, v[146:147]
	global_load_lds_dwordx4 v[232:233], off
	s_mov_b32 m0, s37
	s_nop 0
	global_load_lds_dwordx4 v[234:235], off
	s_waitcnt vmcnt(8)
	s_waitcnt lgkmcnt(0)
	s_barrier
	s_setprio 1
	s_waitcnt lgkmcnt(0)
	v_mfma_f32_16x16x32_bf16 v[62:65], v[86:89], v[198:201], v[62:65]
	v_mfma_f32_16x16x32_bf16 v[58:61], v[130:133], v[198:201], v[58:61]
	v_mfma_f32_16x16x32_bf16 v[46:49], v[86:89], v[206:209], v[46:49]
	v_mfma_f32_16x16x32_bf16 v[42:45], v[130:133], v[206:209], v[42:45]
	v_mfma_f32_16x16x32_bf16 v[30:33], v[86:89], v[214:217], v[30:33]
	v_mfma_f32_16x16x32_bf16 v[26:29], v[130:133], v[214:217], v[26:29]
	v_mfma_f32_16x16x32_bf16 v[18:21], v[86:89], v[222:225], v[18:21]
	v_mfma_f32_16x16x32_bf16 v[10:13], v[130:133], v[222:225], v[10:13]
	v_mfma_f32_16x16x32_bf16 v[62:65], v[126:129], v[202:205], v[62:65]
	v_mfma_f32_16x16x32_bf16 v[58:61], v[138:141], v[202:205], v[58:61]
	v_mfma_f32_16x16x32_bf16 v[46:49], v[126:129], v[210:213], v[46:49]
	v_mfma_f32_16x16x32_bf16 v[42:45], v[138:141], v[210:213], v[42:45]
	v_mfma_f32_16x16x32_bf16 v[30:33], v[126:129], v[218:221], v[30:33]
	v_mfma_f32_16x16x32_bf16 v[26:29], v[138:141], v[218:221], v[26:29]
	v_mfma_f32_16x16x32_bf16 v[18:21], v[126:129], v[226:229], v[18:21]
	v_mfma_f32_16x16x32_bf16 v[10:13], v[138:141], v[226:229], v[10:13]
	s_setprio 0
	s_setprio 1
	v_mfma_f32_16x16x32_bf16 v[54:57], v[182:185], v[198:201], v[54:57]
	v_mfma_f32_16x16x32_bf16 v[50:53], v[190:193], v[198:201], v[50:53]
	v_mfma_f32_16x16x32_bf16 v[38:41], v[182:185], v[206:209], v[38:41]
	v_mfma_f32_16x16x32_bf16 v[34:37], v[190:193], v[206:209], v[34:37]
	v_mfma_f32_16x16x32_bf16 v[22:25], v[182:185], v[214:217], v[22:25]
	v_mfma_f32_16x16x32_bf16 v[14:17], v[190:193], v[214:217], v[14:17]
	v_mfma_f32_16x16x32_bf16 v[6:9], v[182:185], v[222:225], v[6:9]
	v_mfma_f32_16x16x32_bf16 v[2:5], v[190:193], v[222:225], v[2:5]
	v_mfma_f32_16x16x32_bf16 v[54:57], v[186:189], v[202:205], v[54:57]
	v_mfma_f32_16x16x32_bf16 v[50:53], v[194:197], v[202:205], v[50:53]
	v_mfma_f32_16x16x32_bf16 v[38:41], v[186:189], v[210:213], v[38:41]
	v_mfma_f32_16x16x32_bf16 v[34:37], v[194:197], v[210:213], v[34:37]
	v_mfma_f32_16x16x32_bf16 v[22:25], v[186:189], v[218:221], v[22:25]
	v_mfma_f32_16x16x32_bf16 v[14:17], v[194:197], v[218:221], v[14:17]
	v_mfma_f32_16x16x32_bf16 v[6:9], v[186:189], v[226:229], v[6:9]
	v_mfma_f32_16x16x32_bf16 v[2:5], v[194:197], v[226:229], v[2:5]
	s_setprio 0
	s_barrier
	s_add_i32 s56, 0, 0x18000
	s_add_i32 s57, 0, 0x1c000
	v_add_u32_e32 v138, s56, v176
	v_add_u32_e32 v181, s57, v176
	ds_read_b128 v[86:89], v138
	ds_read_b128 v[126:129], v138 offset:1024
	ds_read_b128 v[130:133], v138 offset:2048
	ds_read_b128 v[138:141], v138 offset:3072
	ds_read_b128 v[182:185], v181
	ds_read_b128 v[186:189], v181 offset:1024
	ds_read_b128 v[190:193], v181 offset:2048
	ds_read_b128 v[194:197], v181 offset:3072
	s_add_u32 s22, s28, 0x40000
	s_addc_u32 s23, s29, 0
	s_mov_b32 m0, s38
	v_lshl_add_u64 v[236:237], s[22:23], 0, v[146:147]
	ds_read_b128 v[198:201], v180 offset:32768
	ds_read_b128 v[202:205], v180 offset:33792
	ds_read_b128 v[206:209], v180 offset:34816
	ds_read_b128 v[210:213], v180 offset:35840
	ds_read_b128 v[214:217], v180 offset:36864
	ds_read_b128 v[218:221], v180 offset:37888
	ds_read_b128 v[222:225], v180 offset:38912
	ds_read_b128 v[226:229], v180 offset:39936
	global_load_lds_dwordx4 v[236:237], off
	s_mov_b32 m0, s39
	v_lshl_add_u64 v[236:237], s[22:23], 0, v[148:149]
	global_load_lds_dwordx4 v[236:237], off
	s_waitcnt vmcnt(8)
	s_waitcnt lgkmcnt(0)
	s_barrier
	s_setprio 1
	s_waitcnt lgkmcnt(0)
	v_mfma_f32_16x16x32_bf16 v[142:145], v[86:89], v[198:201], v[142:145]
	v_mfma_f32_16x16x32_bf16 v[134:137], v[130:133], v[198:201], v[134:137]
	v_mfma_f32_16x16x32_bf16 v[118:121], v[86:89], v[206:209], v[118:121]
	v_mfma_f32_16x16x32_bf16 v[110:113], v[130:133], v[206:209], v[110:113]
	v_mfma_f32_16x16x32_bf16 v[102:105], v[86:89], v[214:217], v[102:105]
	v_mfma_f32_16x16x32_bf16 v[94:97], v[130:133], v[214:217], v[94:97]
	v_mfma_f32_16x16x32_bf16 v[82:85], v[86:89], v[222:225], v[82:85]
	v_mfma_f32_16x16x32_bf16 v[74:77], v[130:133], v[222:225], v[74:77]
	v_mfma_f32_16x16x32_bf16 v[142:145], v[126:129], v[202:205], v[142:145]
	v_mfma_f32_16x16x32_bf16 v[134:137], v[138:141], v[202:205], v[134:137]
	v_mfma_f32_16x16x32_bf16 v[118:121], v[126:129], v[210:213], v[118:121]
	v_mfma_f32_16x16x32_bf16 v[110:113], v[138:141], v[210:213], v[110:113]
	v_mfma_f32_16x16x32_bf16 v[102:105], v[126:129], v[218:221], v[102:105]
	v_mfma_f32_16x16x32_bf16 v[94:97], v[138:141], v[218:221], v[94:97]
	v_mfma_f32_16x16x32_bf16 v[82:85], v[126:129], v[226:229], v[82:85]
	v_mfma_f32_16x16x32_bf16 v[74:77], v[138:141], v[226:229], v[74:77]
	s_setprio 0
	s_setprio 1
	v_mfma_f32_16x16x32_bf16 v[122:125], v[182:185], v[198:201], v[122:125]
	v_mfma_f32_16x16x32_bf16 v[114:117], v[190:193], v[198:201], v[114:117]
	v_mfma_f32_16x16x32_bf16 v[106:109], v[182:185], v[206:209], v[106:109]
	v_mfma_f32_16x16x32_bf16 v[98:101], v[190:193], v[206:209], v[98:101]
	v_mfma_f32_16x16x32_bf16 v[90:93], v[182:185], v[214:217], v[90:93]
	v_mfma_f32_16x16x32_bf16 v[78:81], v[190:193], v[214:217], v[78:81]
	v_mfma_f32_16x16x32_bf16 v[70:73], v[182:185], v[222:225], v[70:73]
	v_mfma_f32_16x16x32_bf16 v[66:69], v[190:193], v[222:225], v[66:69]
	v_mfma_f32_16x16x32_bf16 v[122:125], v[186:189], v[202:205], v[122:125]
	v_mfma_f32_16x16x32_bf16 v[114:117], v[194:197], v[202:205], v[114:117]
	v_mfma_f32_16x16x32_bf16 v[106:109], v[186:189], v[210:213], v[106:109]
	v_mfma_f32_16x16x32_bf16 v[98:101], v[194:197], v[210:213], v[98:101]
	v_mfma_f32_16x16x32_bf16 v[90:93], v[186:189], v[218:221], v[90:93]
	v_mfma_f32_16x16x32_bf16 v[78:81], v[194:197], v[218:221], v[78:81]
	v_mfma_f32_16x16x32_bf16 v[70:73], v[186:189], v[226:229], v[70:73]
	v_mfma_f32_16x16x32_bf16 v[66:69], v[194:197], v[226:229], v[66:69]
	s_setprio 0
	s_barrier
	s_add_i32 s22, s56, s35
	v_lshl_add_u64 v[174:175], v[174:175], 0, s[8:9]
	s_mov_b32 m0, s22
	ds_read_b128 v[198:201], v180 offset:49152
	ds_read_b128 v[202:205], v180 offset:50176
	ds_read_b128 v[206:209], v180 offset:51200
	ds_read_b128 v[210:213], v180 offset:52224
	ds_read_b128 v[214:217], v180 offset:53248
	ds_read_b128 v[218:221], v180 offset:54272
	ds_read_b128 v[222:225], v180 offset:55296
	ds_read_b128 v[226:229], v180 offset:56320
	global_load_lds_dwordx4 v[174:175], off
	s_add_i32 m0, s22, 0x2000
	s_add_u32 s22, s26, 0x40080
	v_lshl_add_u64 v[174:175], v[230:231], 0, s[8:9]
	s_addc_u32 s23, s27, 0
	s_add_i32 s26, s57, s35
	global_load_lds_dwordx4 v[174:175], off
	s_mov_b32 m0, s26
	v_lshl_add_u64 v[174:175], s[22:23], 0, v[146:147]
	global_load_lds_dwordx4 v[174:175], off
	s_add_i32 m0, s26, 0x2000
	v_lshl_add_u64 v[174:175], s[22:23], 0, v[148:149]
	global_load_lds_dwordx4 v[174:175], off
	s_mov_b32 m0, s45
	v_lshl_add_u64 v[174:175], v[232:233], 0, s[8:9]
	global_load_lds_dwordx4 v[174:175], off
	s_mov_b32 m0, s46
	v_lshl_add_u64 v[174:175], v[234:235], 0, s[8:9]
	global_load_lds_dwordx4 v[174:175], off
	s_waitcnt vmcnt(8)
	s_waitcnt lgkmcnt(0)
	s_barrier
	s_setprio 1
	s_waitcnt lgkmcnt(0)
	v_mfma_f32_16x16x32_bf16 v[62:65], v[86:89], v[198:201], v[62:65]
	v_mfma_f32_16x16x32_bf16 v[58:61], v[130:133], v[198:201], v[58:61]
	v_mfma_f32_16x16x32_bf16 v[46:49], v[86:89], v[206:209], v[46:49]
	v_mfma_f32_16x16x32_bf16 v[42:45], v[130:133], v[206:209], v[42:45]
	v_mfma_f32_16x16x32_bf16 v[30:33], v[86:89], v[214:217], v[30:33]
	v_mfma_f32_16x16x32_bf16 v[26:29], v[130:133], v[214:217], v[26:29]
	v_mfma_f32_16x16x32_bf16 v[18:21], v[86:89], v[222:225], v[18:21]
	v_mfma_f32_16x16x32_bf16 v[10:13], v[130:133], v[222:225], v[10:13]
	v_mfma_f32_16x16x32_bf16 v[62:65], v[126:129], v[202:205], v[62:65]
	v_mfma_f32_16x16x32_bf16 v[58:61], v[138:141], v[202:205], v[58:61]
	v_mfma_f32_16x16x32_bf16 v[46:49], v[126:129], v[210:213], v[46:49]
	v_mfma_f32_16x16x32_bf16 v[42:45], v[138:141], v[210:213], v[42:45]
	v_mfma_f32_16x16x32_bf16 v[30:33], v[126:129], v[218:221], v[30:33]
	v_mfma_f32_16x16x32_bf16 v[26:29], v[138:141], v[218:221], v[26:29]
	v_mfma_f32_16x16x32_bf16 v[18:21], v[126:129], v[226:229], v[18:21]
	v_mfma_f32_16x16x32_bf16 v[10:13], v[138:141], v[226:229], v[10:13]
	s_setprio 0
	s_setprio 1
	v_mfma_f32_16x16x32_bf16 v[54:57], v[182:185], v[198:201], v[54:57]
	v_mfma_f32_16x16x32_bf16 v[50:53], v[190:193], v[198:201], v[50:53]
	v_mfma_f32_16x16x32_bf16 v[38:41], v[182:185], v[206:209], v[38:41]
	v_mfma_f32_16x16x32_bf16 v[34:37], v[190:193], v[206:209], v[34:37]
	v_mfma_f32_16x16x32_bf16 v[22:25], v[182:185], v[214:217], v[22:25]
	v_mfma_f32_16x16x32_bf16 v[14:17], v[190:193], v[214:217], v[14:17]
	v_mfma_f32_16x16x32_bf16 v[6:9], v[182:185], v[222:225], v[6:9]
	v_mfma_f32_16x16x32_bf16 v[2:5], v[190:193], v[222:225], v[2:5]
	v_mfma_f32_16x16x32_bf16 v[54:57], v[186:189], v[202:205], v[54:57]
	v_mfma_f32_16x16x32_bf16 v[50:53], v[194:197], v[202:205], v[50:53]
	v_mfma_f32_16x16x32_bf16 v[38:41], v[186:189], v[210:213], v[38:41]
	v_mfma_f32_16x16x32_bf16 v[34:37], v[194:197], v[210:213], v[34:37]
	v_mfma_f32_16x16x32_bf16 v[22:25], v[186:189], v[218:221], v[22:25]
	v_mfma_f32_16x16x32_bf16 v[14:17], v[194:197], v[218:221], v[14:17]
	v_mfma_f32_16x16x32_bf16 v[6:9], v[186:189], v[226:229], v[6:9]
	v_mfma_f32_16x16x32_bf16 v[2:5], v[194:197], v[226:229], v[2:5]
	s_setprio 0
	s_barrier
	s_add_i32 s55, s55, 2
	s_add_u32 s53, s53, 0x100
	s_addc_u32 s54, s54, 0
	s_cmp_gt_u32 s55, 13
	s_mov_b64 s[22:23], s[24:25]
	s_cbranch_scc0 .LBB0_2328
	s_and_b64 vcc, exec, s[10:11]
	s_cbranch_vccz .LBB0_2331
	s_barrier

.LBB0_2486:
	ds_read_b128 v[154:157], v151
	ds_read_b128 v[158:161], v151 offset:1024
	ds_read_b128 v[162:165], v151 offset:2048
	ds_read_b128 v[166:169], v151 offset:3072
	ds_read_b128 v[170:173], v152
	ds_read_b128 v[174:177], v152 offset:1024
	ds_read_b128 v[178:181], v152 offset:2048
	ds_read_b128 v[182:185], v152 offset:3072
	s_add_u32 s26, s24, 0xfffc0080
	s_addc_u32 s27, s25, -1
	s_cmp_eq_u32 s52, 12
	s_cselect_b32 s29, s17, s27
	s_cselect_b32 s28, s48, s26
	s_cselect_b32 s27, s15, s51
	s_cselect_b32 s26, s49, s50
	v_lshl_add_u64 v[146:147], s[24:25], 0, v[138:139]
	s_add_i32 m0, s23, 0xc000
	ds_read_b128 v[186:189], v153
	ds_read_b128 v[190:193], v153 offset:1024
	ds_read_b128 v[194:197], v153 offset:2048
	ds_read_b128 v[198:201], v153 offset:3072
	ds_read_b128 v[202:205], v153 offset:4096
	ds_read_b128 v[206:209], v153 offset:5120
	ds_read_b128 v[210:213], v153 offset:6144
	ds_read_b128 v[214:217], v153 offset:7168
	global_load_lds_dwordx4 v[146:147], off
	s_add_i32 m0, s23, 0xe000
	v_lshl_add_u64 v[146:147], s[24:25], 0, v[140:141]
	global_load_lds_dwordx4 v[146:147], off
	s_waitcnt vmcnt(8)
	s_waitcnt lgkmcnt(0)
	s_barrier
	s_setprio 1
	s_waitcnt lgkmcnt(0)
	v_mfma_f32_16x16x32_bf16 v[126:129], v[154:157], v[186:189], v[126:129]
	v_mfma_f32_16x16x32_bf16 v[122:125], v[162:165], v[186:189], v[122:125]
	v_mfma_f32_16x16x32_bf16 v[110:113], v[154:157], v[194:197], v[110:113]
	v_mfma_f32_16x16x32_bf16 v[106:109], v[162:165], v[194:197], v[106:109]
	v_mfma_f32_16x16x32_bf16 v[94:97], v[154:157], v[202:205], v[94:97]
	v_mfma_f32_16x16x32_bf16 v[90:93], v[162:165], v[202:205], v[90:93]
	v_mfma_f32_16x16x32_bf16 v[78:81], v[154:157], v[210:213], v[78:81]
	v_mfma_f32_16x16x32_bf16 v[74:77], v[162:165], v[210:213], v[74:77]
	v_mfma_f32_16x16x32_bf16 v[126:129], v[158:161], v[190:193], v[126:129]
	v_mfma_f32_16x16x32_bf16 v[122:125], v[166:169], v[190:193], v[122:125]
	v_mfma_f32_16x16x32_bf16 v[110:113], v[158:161], v[198:201], v[110:113]
	v_mfma_f32_16x16x32_bf16 v[106:109], v[166:169], v[198:201], v[106:109]
	v_mfma_f32_16x16x32_bf16 v[94:97], v[158:161], v[206:209], v[94:97]
	v_mfma_f32_16x16x32_bf16 v[90:93], v[166:169], v[206:209], v[90:93]
	v_mfma_f32_16x16x32_bf16 v[78:81], v[158:161], v[214:217], v[78:81]
	v_mfma_f32_16x16x32_bf16 v[74:77], v[166:169], v[214:217], v[74:77]
	s_setprio 0
	s_setprio 1
	v_mfma_f32_16x16x32_bf16 v[118:121], v[170:173], v[186:189], v[118:121]
	v_mfma_f32_16x16x32_bf16 v[114:117], v[178:181], v[186:189], v[114:117]
	v_mfma_f32_16x16x32_bf16 v[102:105], v[170:173], v[194:197], v[102:105]
	v_mfma_f32_16x16x32_bf16 v[98:101], v[178:181], v[194:197], v[98:101]
	v_mfma_f32_16x16x32_bf16 v[86:89], v[170:173], v[202:205], v[86:89]
	v_mfma_f32_16x16x32_bf16 v[82:85], v[178:181], v[202:205], v[82:85]
	v_mfma_f32_16x16x32_bf16 v[70:73], v[170:173], v[210:213], v[70:73]
	v_mfma_f32_16x16x32_bf16 v[66:69], v[178:181], v[210:213], v[66:69]
	v_mfma_f32_16x16x32_bf16 v[118:121], v[174:177], v[190:193], v[118:121]
	v_mfma_f32_16x16x32_bf16 v[114:117], v[182:185], v[190:193], v[114:117]
	v_mfma_f32_16x16x32_bf16 v[102:105], v[174:177], v[198:201], v[102:105]
	v_mfma_f32_16x16x32_bf16 v[98:101], v[182:185], v[198:201], v[98:101]
	v_mfma_f32_16x16x32_bf16 v[86:89], v[174:177], v[206:209], v[86:89]
	v_mfma_f32_16x16x32_bf16 v[82:85], v[182:185], v[206:209], v[82:85]
	v_mfma_f32_16x16x32_bf16 v[70:73], v[174:177], v[214:217], v[70:73]
	v_mfma_f32_16x16x32_bf16 v[66:69], v[182:185], v[214:217], v[66:69]
	s_setprio 0
	s_barrier
	s_add_i32 s53, s45, s34
	v_lshl_add_u64 v[146:147], s[26:27], 0, v[134:135]
	s_mov_b32 m0, s53
	ds_read_b128 v[186:189], v153 offset:16384
	ds_read_b128 v[190:193], v153 offset:17408
	ds_read_b128 v[194:197], v153 offset:18432
	ds_read_b128 v[198:201], v153 offset:19456
	ds_read_b128 v[202:205], v153 offset:20480
	ds_read_b128 v[206:209], v153 offset:21504
	ds_read_b128 v[210:213], v153 offset:22528
	ds_read_b128 v[214:217], v153 offset:23552
	global_load_lds_dwordx4 v[146:147], off
	s_add_i32 m0, s53, 0x2000
	s_add_u32 s54, s26, 0x40000
	v_lshl_add_u64 v[218:219], s[26:27], 0, v[130:131]
	s_addc_u32 s55, s27, 0
	s_add_i32 s53, s46, s34
	global_load_lds_dwordx4 v[218:219], off
	v_lshl_add_u64 v[220:221], s[54:55], 0, v[134:135]
	s_mov_b32 m0, s53
	v_lshl_add_u64 v[222:223], s[28:29], 0, v[132:133]
	global_load_lds_dwordx4 v[220:221], off
	s_add_i32 m0, s53, 0x2000
	v_lshl_add_u64 v[220:221], s[54:55], 0, v[130:131]
	global_load_lds_dwordx4 v[220:221], off
	s_mov_b32 m0, s23
	v_lshl_add_u64 v[220:221], s[28:29], 0, v[136:137]
	global_load_lds_dwordx4 v[220:221], off
	s_mov_b32 m0, s37
	s_nop 0
	global_load_lds_dwordx4 v[222:223], off
	s_waitcnt vmcnt(8)
	s_waitcnt lgkmcnt(0)
	s_barrier
	s_setprio 1
	s_waitcnt lgkmcnt(0)
	v_mfma_f32_16x16x32_bf16 v[62:65], v[154:157], v[186:189], v[62:65]
	v_mfma_f32_16x16x32_bf16 v[58:61], v[162:165], v[186:189], v[58:61]
	v_mfma_f32_16x16x32_bf16 v[46:49], v[154:157], v[194:197], v[46:49]
	v_mfma_f32_16x16x32_bf16 v[42:45], v[162:165], v[194:197], v[42:45]
	v_mfma_f32_16x16x32_bf16 v[30:33], v[154:157], v[202:205], v[30:33]
	v_mfma_f32_16x16x32_bf16 v[26:29], v[162:165], v[202:205], v[26:29]
	v_mfma_f32_16x16x32_bf16 v[14:17], v[154:157], v[210:213], v[14:17]
	v_mfma_f32_16x16x32_bf16 v[10:13], v[162:165], v[210:213], v[10:13]
	v_mfma_f32_16x16x32_bf16 v[62:65], v[158:161], v[190:193], v[62:65]
	v_mfma_f32_16x16x32_bf16 v[58:61], v[166:169], v[190:193], v[58:61]
	v_mfma_f32_16x16x32_bf16 v[46:49], v[158:161], v[198:201], v[46:49]
	v_mfma_f32_16x16x32_bf16 v[42:45], v[166:169], v[198:201], v[42:45]
	v_mfma_f32_16x16x32_bf16 v[30:33], v[158:161], v[206:209], v[30:33]
	v_mfma_f32_16x16x32_bf16 v[26:29], v[166:169], v[206:209], v[26:29]
	v_mfma_f32_16x16x32_bf16 v[14:17], v[158:161], v[214:217], v[14:17]
	v_mfma_f32_16x16x32_bf16 v[10:13], v[166:169], v[214:217], v[10:13]
	s_setprio 0
	s_setprio 1
	v_mfma_f32_16x16x32_bf16 v[54:57], v[170:173], v[186:189], v[54:57]
	v_mfma_f32_16x16x32_bf16 v[50:53], v[178:181], v[186:189], v[50:53]
	v_mfma_f32_16x16x32_bf16 v[38:41], v[170:173], v[194:197], v[38:41]
	v_mfma_f32_16x16x32_bf16 v[34:37], v[178:181], v[194:197], v[34:37]
	v_mfma_f32_16x16x32_bf16 v[22:25], v[170:173], v[202:205], v[22:25]
	v_mfma_f32_16x16x32_bf16 v[18:21], v[178:181], v[202:205], v[18:21]
	v_mfma_f32_16x16x32_bf16 v[6:9], v[170:173], v[210:213], v[6:9]
	v_mfma_f32_16x16x32_bf16 v[2:5], v[178:181], v[210:213], v[2:5]
	v_mfma_f32_16x16x32_bf16 v[54:57], v[174:177], v[190:193], v[54:57]
	v_mfma_f32_16x16x32_bf16 v[50:53], v[182:185], v[190:193], v[50:53]
	v_mfma_f32_16x16x32_bf16 v[38:41], v[174:177], v[198:201], v[38:41]
	v_mfma_f32_16x16x32_bf16 v[34:37], v[182:185], v[198:201], v[34:37]
	v_mfma_f32_16x16x32_bf16 v[22:25], v[174:177], v[206:209], v[22:25]
	v_mfma_f32_16x16x32_bf16 v[18:21], v[182:185], v[206:209], v[18:21]
	v_mfma_f32_16x16x32_bf16 v[6:9], v[174:177], v[214:217], v[6:9]
	v_mfma_f32_16x16x32_bf16 v[2:5], v[182:185], v[214:217], v[2:5]
	s_setprio 0
	s_barrier
	s_add_i32 s53, 0, 0x18000
	s_add_i32 s54, 0, 0x1c000
	v_add_u32_e32 v166, s53, v149
	v_add_u32_e32 v182, s54, v149
	ds_read_b128 v[154:157], v166
	ds_read_b128 v[158:161], v166 offset:1024
	ds_read_b128 v[162:165], v166 offset:2048
	ds_read_b128 v[166:169], v166 offset:3072
	ds_read_b128 v[170:173], v182
	ds_read_b128 v[174:177], v182 offset:1024
	ds_read_b128 v[178:181], v182 offset:2048
	ds_read_b128 v[182:185], v182 offset:3072
	s_add_u32 s28, s28, 0x40000
	s_addc_u32 s29, s29, 0
	s_mov_b32 m0, s38
	v_lshl_add_u64 v[224:225], s[28:29], 0, v[136:137]
	ds_read_b128 v[186:189], v153 offset:32768
	ds_read_b128 v[190:193], v153 offset:33792
	ds_read_b128 v[194:197], v153 offset:34816
	ds_read_b128 v[198:201], v153 offset:35840
	ds_read_b128 v[202:205], v153 offset:36864
	ds_read_b128 v[206:209], v153 offset:37888
	ds_read_b128 v[210:213], v153 offset:38912
	ds_read_b128 v[214:217], v153 offset:39936
	global_load_lds_dwordx4 v[224:225], off
	s_mov_b32 m0, s39
	v_lshl_add_u64 v[224:225], s[28:29], 0, v[132:133]
	global_load_lds_dwordx4 v[224:225], off
	s_waitcnt vmcnt(8)
	s_waitcnt lgkmcnt(0)
	s_barrier
	s_setprio 1
	s_waitcnt lgkmcnt(0)
	v_mfma_f32_16x16x32_bf16 v[126:129], v[154:157], v[186:189], v[126:129]
	v_mfma_f32_16x16x32_bf16 v[122:125], v[162:165], v[186:189], v[122:125]
	v_mfma_f32_16x16x32_bf16 v[110:113], v[154:157], v[194:197], v[110:113]
	v_mfma_f32_16x16x32_bf16 v[106:109], v[162:165], v[194:197], v[106:109]
	v_mfma_f32_16x16x32_bf16 v[94:97], v[154:157], v[202:205], v[94:97]
	v_mfma_f32_16x16x32_bf16 v[90:93], v[162:165], v[202:205], v[90:93]
	v_mfma_f32_16x16x32_bf16 v[78:81], v[154:157], v[210:213], v[78:81]
	v_mfma_f32_16x16x32_bf16 v[74:77], v[162:165], v[210:213], v[74:77]
	v_mfma_f32_16x16x32_bf16 v[126:129], v[158:161], v[190:193], v[126:129]
	v_mfma_f32_16x16x32_bf16 v[122:125], v[166:169], v[190:193], v[122:125]
	v_mfma_f32_16x16x32_bf16 v[110:113], v[158:161], v[198:201], v[110:113]
	v_mfma_f32_16x16x32_bf16 v[106:109], v[166:169], v[198:201], v[106:109]
	v_mfma_f32_16x16x32_bf16 v[94:97], v[158:161], v[206:209], v[94:97]
	v_mfma_f32_16x16x32_bf16 v[90:93], v[166:169], v[206:209], v[90:93]
	v_mfma_f32_16x16x32_bf16 v[78:81], v[158:161], v[214:217], v[78:81]
	v_mfma_f32_16x16x32_bf16 v[74:77], v[166:169], v[214:217], v[74:77]
	s_setprio 0
	s_setprio 1
	v_mfma_f32_16x16x32_bf16 v[118:121], v[170:173], v[186:189], v[118:121]
	v_mfma_f32_16x16x32_bf16 v[114:117], v[178:181], v[186:189], v[114:117]
	v_mfma_f32_16x16x32_bf16 v[102:105], v[170:173], v[194:197], v[102:105]
	v_mfma_f32_16x16x32_bf16 v[98:101], v[178:181], v[194:197], v[98:101]
	v_mfma_f32_16x16x32_bf16 v[86:89], v[170:173], v[202:205], v[86:89]
	v_mfma_f32_16x16x32_bf16 v[82:85], v[178:181], v[202:205], v[82:85]
	v_mfma_f32_16x16x32_bf16 v[70:73], v[170:173], v[210:213], v[70:73]
	v_mfma_f32_16x16x32_bf16 v[66:69], v[178:181], v[210:213], v[66:69]
	v_mfma_f32_16x16x32_bf16 v[118:121], v[174:177], v[190:193], v[118:121]
	v_mfma_f32_16x16x32_bf16 v[114:117], v[182:185], v[190:193], v[114:117]
	v_mfma_f32_16x16x32_bf16 v[102:105], v[174:177], v[198:201], v[102:105]
	v_mfma_f32_16x16x32_bf16 v[98:101], v[182:185], v[198:201], v[98:101]
	v_mfma_f32_16x16x32_bf16 v[86:89], v[174:177], v[206:209], v[86:89]
	v_mfma_f32_16x16x32_bf16 v[82:85], v[182:185], v[206:209], v[82:85]
	v_mfma_f32_16x16x32_bf16 v[70:73], v[174:177], v[214:217], v[70:73]
	v_mfma_f32_16x16x32_bf16 v[66:69], v[182:185], v[214:217], v[66:69]
	s_setprio 0
	s_barrier
	s_add_i32 s28, s53, s34
	v_lshl_add_u64 v[146:147], v[146:147], 0, s[10:11]
	s_mov_b32 m0, s28
	ds_read_b128 v[186:189], v153 offset:49152
	ds_read_b128 v[190:193], v153 offset:50176
	ds_read_b128 v[194:197], v153 offset:51200
	ds_read_b128 v[198:201], v153 offset:52224
	ds_read_b128 v[202:205], v153 offset:53248
	ds_read_b128 v[206:209], v153 offset:54272
	ds_read_b128 v[210:213], v153 offset:55296
	ds_read_b128 v[214:217], v153 offset:56320
	global_load_lds_dwordx4 v[146:147], off
	s_add_i32 m0, s28, 0x2000
	s_add_u32 s26, s26, 0x40080
	v_lshl_add_u64 v[146:147], v[218:219], 0, s[10:11]
	s_addc_u32 s27, s27, 0
	s_add_i32 s28, s54, s34
	global_load_lds_dwordx4 v[146:147], off
	s_mov_b32 m0, s28
	v_lshl_add_u64 v[146:147], s[26:27], 0, v[134:135]
	global_load_lds_dwordx4 v[146:147], off
	s_add_i32 m0, s28, 0x2000
	v_lshl_add_u64 v[146:147], s[26:27], 0, v[130:131]
	global_load_lds_dwordx4 v[146:147], off
	s_mov_b32 m0, s42
	v_lshl_add_u64 v[146:147], v[220:221], 0, s[10:11]
	global_load_lds_dwordx4 v[146:147], off
	s_mov_b32 m0, s43
	v_lshl_add_u64 v[146:147], v[222:223], 0, s[10:11]
	global_load_lds_dwordx4 v[146:147], off
	s_waitcnt vmcnt(8)
	s_waitcnt lgkmcnt(0)
	s_barrier
	s_setprio 1
	s_waitcnt lgkmcnt(0)
	v_mfma_f32_16x16x32_bf16 v[62:65], v[154:157], v[186:189], v[62:65]
	v_mfma_f32_16x16x32_bf16 v[58:61], v[162:165], v[186:189], v[58:61]
	v_mfma_f32_16x16x32_bf16 v[46:49], v[154:157], v[194:197], v[46:49]
	v_mfma_f32_16x16x32_bf16 v[42:45], v[162:165], v[194:197], v[42:45]
	v_mfma_f32_16x16x32_bf16 v[30:33], v[154:157], v[202:205], v[30:33]
	v_mfma_f32_16x16x32_bf16 v[26:29], v[162:165], v[202:205], v[26:29]
	v_mfma_f32_16x16x32_bf16 v[14:17], v[154:157], v[210:213], v[14:17]
	v_mfma_f32_16x16x32_bf16 v[10:13], v[162:165], v[210:213], v[10:13]
	v_mfma_f32_16x16x32_bf16 v[62:65], v[158:161], v[190:193], v[62:65]
	v_mfma_f32_16x16x32_bf16 v[58:61], v[166:169], v[190:193], v[58:61]
	v_mfma_f32_16x16x32_bf16 v[46:49], v[158:161], v[198:201], v[46:49]
	v_mfma_f32_16x16x32_bf16 v[42:45], v[166:169], v[198:201], v[42:45]
	v_mfma_f32_16x16x32_bf16 v[30:33], v[158:161], v[206:209], v[30:33]
	v_mfma_f32_16x16x32_bf16 v[26:29], v[166:169], v[206:209], v[26:29]
	v_mfma_f32_16x16x32_bf16 v[14:17], v[158:161], v[214:217], v[14:17]
	v_mfma_f32_16x16x32_bf16 v[10:13], v[166:169], v[214:217], v[10:13]
	s_setprio 0
	s_setprio 1
	v_mfma_f32_16x16x32_bf16 v[54:57], v[170:173], v[186:189], v[54:57]
	v_mfma_f32_16x16x32_bf16 v[50:53], v[178:181], v[186:189], v[50:53]
	v_mfma_f32_16x16x32_bf16 v[38:41], v[170:173], v[194:197], v[38:41]
	v_mfma_f32_16x16x32_bf16 v[34:37], v[178:181], v[194:197], v[34:37]
	v_mfma_f32_16x16x32_bf16 v[22:25], v[170:173], v[202:205], v[22:25]
	v_mfma_f32_16x16x32_bf16 v[18:21], v[178:181], v[202:205], v[18:21]
	v_mfma_f32_16x16x32_bf16 v[6:9], v[170:173], v[210:213], v[6:9]
	v_mfma_f32_16x16x32_bf16 v[2:5], v[178:181], v[210:213], v[2:5]
	v_mfma_f32_16x16x32_bf16 v[54:57], v[174:177], v[190:193], v[54:57]
	v_mfma_f32_16x16x32_bf16 v[50:53], v[182:185], v[190:193], v[50:53]
	v_mfma_f32_16x16x32_bf16 v[38:41], v[174:177], v[198:201], v[38:41]
	v_mfma_f32_16x16x32_bf16 v[34:37], v[182:185], v[198:201], v[34:37]
	v_mfma_f32_16x16x32_bf16 v[22:25], v[174:177], v[206:209], v[22:25]
	v_mfma_f32_16x16x32_bf16 v[18:21], v[182:185], v[206:209], v[18:21]
	v_mfma_f32_16x16x32_bf16 v[6:9], v[174:177], v[214:217], v[6:9]
	v_mfma_f32_16x16x32_bf16 v[2:5], v[182:185], v[214:217], v[2:5]
	s_setprio 0
	s_barrier
	s_add_i32 s52, s52, 2
	s_add_u32 s24, s24, 0x100
	s_addc_u32 s25, s25, 0
	s_add_u32 s50, s50, 0x100
	s_addc_u32 s51, s51, 0
	s_cmp_gt_u32 s52, 13
	s_cbranch_scc0 .LBB0_2486
	s_and_b64 vcc, exec, s[12:13]
	s_cbranch_vccz .LBB0_2489
	s_barrier

.LBB0_2583:
	ds_read_b128 v[158:161], v178
	ds_read_b128 v[162:165], v178 offset:1024
	ds_read_b128 v[166:169], v178 offset:2048
	ds_read_b128 v[170:173], v178 offset:3072
	ds_read_b128 v[182:185], v179
	ds_read_b128 v[186:189], v179 offset:1024
	ds_read_b128 v[190:193], v179 offset:2048
	ds_read_b128 v[194:197], v179 offset:3072
	s_add_u32 s18, s16, 0x100
	s_addc_u32 s19, s17, 0
	s_cmp_eq_u32 s51, 40
	s_cselect_b32 s23, s7, s19
	s_cselect_b32 s22, s6, s18
	s_cselect_b32 s21, s15, s50
	s_cselect_b32 s20, s14, s2
	v_lshl_add_u64 v[174:175], s[16:17], 0, v[150:151]
	s_add_i32 m0, s29, 0xc000
	ds_read_b128 v[198:201], v180
	ds_read_b128 v[202:205], v180 offset:1024
	ds_read_b128 v[206:209], v180 offset:2048
	ds_read_b128 v[210:213], v180 offset:3072
	ds_read_b128 v[214:217], v180 offset:4096
	ds_read_b128 v[218:221], v180 offset:5120
	ds_read_b128 v[222:225], v180 offset:6144
	ds_read_b128 v[226:229], v180 offset:7168
	global_load_lds_dwordx4 v[174:175], off
	s_add_i32 m0, s29, 0xe000
	v_lshl_add_u64 v[174:175], s[16:17], 0, v[152:153]
	global_load_lds_dwordx4 v[174:175], off
	s_waitcnt vmcnt(8)
	s_waitcnt lgkmcnt(0)
	s_barrier
	s_setprio 1
	s_waitcnt lgkmcnt(0)
	v_mfma_f32_16x16x32_bf16 v[126:129], v[158:161], v[198:201], v[126:129]
	v_mfma_f32_16x16x32_bf16 v[122:125], v[166:169], v[198:201], v[122:125]
	v_mfma_f32_16x16x32_bf16 v[114:117], v[158:161], v[206:209], v[114:117]
	v_mfma_f32_16x16x32_bf16 v[106:109], v[166:169], v[206:209], v[106:109]
	v_mfma_f32_16x16x32_bf16 v[98:101], v[158:161], v[214:217], v[98:101]
	v_mfma_f32_16x16x32_bf16 v[90:93], v[166:169], v[214:217], v[90:93]
	v_mfma_f32_16x16x32_bf16 v[78:81], v[158:161], v[222:225], v[78:81]
	v_mfma_f32_16x16x32_bf16 v[74:77], v[166:169], v[222:225], v[74:77]
	v_mfma_f32_16x16x32_bf16 v[126:129], v[162:165], v[202:205], v[126:129]
	v_mfma_f32_16x16x32_bf16 v[122:125], v[170:173], v[202:205], v[122:125]
	v_mfma_f32_16x16x32_bf16 v[114:117], v[162:165], v[210:213], v[114:117]
	v_mfma_f32_16x16x32_bf16 v[106:109], v[170:173], v[210:213], v[106:109]
	v_mfma_f32_16x16x32_bf16 v[98:101], v[162:165], v[218:221], v[98:101]
	v_mfma_f32_16x16x32_bf16 v[90:93], v[170:173], v[218:221], v[90:93]
	v_mfma_f32_16x16x32_bf16 v[78:81], v[162:165], v[226:229], v[78:81]
	v_mfma_f32_16x16x32_bf16 v[74:77], v[170:173], v[226:229], v[74:77]
	s_setprio 0
	s_setprio 1
	v_mfma_f32_16x16x32_bf16 v[118:121], v[182:185], v[198:201], v[118:121]
	v_mfma_f32_16x16x32_bf16 v[110:113], v[190:193], v[198:201], v[110:113]
	v_mfma_f32_16x16x32_bf16 v[102:105], v[182:185], v[206:209], v[102:105]
	v_mfma_f32_16x16x32_bf16 v[94:97], v[190:193], v[206:209], v[94:97]
	v_mfma_f32_16x16x32_bf16 v[86:89], v[182:185], v[214:217], v[86:89]
	v_mfma_f32_16x16x32_bf16 v[82:85], v[190:193], v[214:217], v[82:85]
	v_mfma_f32_16x16x32_bf16 v[70:73], v[182:185], v[222:225], v[70:73]
	v_mfma_f32_16x16x32_bf16 v[66:69], v[190:193], v[222:225], v[66:69]
	v_mfma_f32_16x16x32_bf16 v[118:121], v[186:189], v[202:205], v[118:121]
	v_mfma_f32_16x16x32_bf16 v[110:113], v[194:197], v[202:205], v[110:113]
	v_mfma_f32_16x16x32_bf16 v[102:105], v[186:189], v[210:213], v[102:105]
	v_mfma_f32_16x16x32_bf16 v[94:97], v[194:197], v[210:213], v[94:97]
	v_mfma_f32_16x16x32_bf16 v[86:89], v[186:189], v[218:221], v[86:89]
	v_mfma_f32_16x16x32_bf16 v[82:85], v[194:197], v[218:221], v[82:85]
	v_mfma_f32_16x16x32_bf16 v[70:73], v[186:189], v[226:229], v[70:73]
	v_mfma_f32_16x16x32_bf16 v[66:69], v[194:197], v[226:229], v[66:69]
	s_setprio 0
	s_barrier
	s_add_i32 s16, s43, s28
	v_lshl_add_u64 v[174:175], s[20:21], 0, v[130:131]
	s_mov_b32 m0, s16
	ds_read_b128 v[198:201], v180 offset:16384
	ds_read_b128 v[202:205], v180 offset:17408
	ds_read_b128 v[206:209], v180 offset:18432
	ds_read_b128 v[210:213], v180 offset:19456
	ds_read_b128 v[214:217], v180 offset:20480
	ds_read_b128 v[218:221], v180 offset:21504
	ds_read_b128 v[222:225], v180 offset:22528
	ds_read_b128 v[226:229], v180 offset:23552
	global_load_lds_dwordx4 v[174:175], off
	s_add_i32 m0, s16, 0x2000
	s_add_u32 s16, s20, 0xb0000
	v_lshl_add_u64 v[230:231], s[20:21], 0, v[132:133]
	s_addc_u32 s17, s21, 0
	s_add_i32 s52, s44, s28
	global_load_lds_dwordx4 v[230:231], off
	v_lshl_add_u64 v[232:233], s[16:17], 0, v[130:131]
	s_mov_b32 m0, s52
	v_lshl_add_u64 v[234:235], s[22:23], 0, v[132:133]
	global_load_lds_dwordx4 v[232:233], off
	s_add_i32 m0, s52, 0x2000
	v_lshl_add_u64 v[232:233], s[16:17], 0, v[132:133]
	global_load_lds_dwordx4 v[232:233], off
	s_mov_b32 m0, s29
	v_lshl_add_u64 v[232:233], s[22:23], 0, v[130:131]
	global_load_lds_dwordx4 v[232:233], off
	s_mov_b32 m0, s30
	s_nop 0
	global_load_lds_dwordx4 v[234:235], off
	s_waitcnt vmcnt(8)
	s_waitcnt lgkmcnt(0)
	s_barrier
	s_setprio 1
	s_waitcnt lgkmcnt(0)
	v_mfma_f32_16x16x32_bf16 v[62:65], v[158:161], v[198:201], v[62:65]
	v_mfma_f32_16x16x32_bf16 v[58:61], v[166:169], v[198:201], v[58:61]
	v_mfma_f32_16x16x32_bf16 v[46:49], v[158:161], v[206:209], v[46:49]
	v_mfma_f32_16x16x32_bf16 v[42:45], v[166:169], v[206:209], v[42:45]
	v_mfma_f32_16x16x32_bf16 v[34:37], v[158:161], v[214:217], v[34:37]
	v_mfma_f32_16x16x32_bf16 v[26:29], v[166:169], v[214:217], v[26:29]
	v_mfma_f32_16x16x32_bf16 v[18:21], v[158:161], v[222:225], v[18:21]
	v_mfma_f32_16x16x32_bf16 v[10:13], v[166:169], v[222:225], v[10:13]
	v_mfma_f32_16x16x32_bf16 v[62:65], v[162:165], v[202:205], v[62:65]
	v_mfma_f32_16x16x32_bf16 v[58:61], v[170:173], v[202:205], v[58:61]
	v_mfma_f32_16x16x32_bf16 v[46:49], v[162:165], v[210:213], v[46:49]
	v_mfma_f32_16x16x32_bf16 v[42:45], v[170:173], v[210:213], v[42:45]
	v_mfma_f32_16x16x32_bf16 v[34:37], v[162:165], v[218:221], v[34:37]
	v_mfma_f32_16x16x32_bf16 v[26:29], v[170:173], v[218:221], v[26:29]
	v_mfma_f32_16x16x32_bf16 v[18:21], v[162:165], v[226:229], v[18:21]
	v_mfma_f32_16x16x32_bf16 v[10:13], v[170:173], v[226:229], v[10:13]
	s_setprio 0
	s_setprio 1
	v_mfma_f32_16x16x32_bf16 v[54:57], v[182:185], v[198:201], v[54:57]
	v_mfma_f32_16x16x32_bf16 v[50:53], v[190:193], v[198:201], v[50:53]
	v_mfma_f32_16x16x32_bf16 v[38:41], v[182:185], v[206:209], v[38:41]
	v_mfma_f32_16x16x32_bf16 v[30:33], v[190:193], v[206:209], v[30:33]
	v_mfma_f32_16x16x32_bf16 v[22:25], v[182:185], v[214:217], v[22:25]
	v_mfma_f32_16x16x32_bf16 v[14:17], v[190:193], v[214:217], v[14:17]
	v_mfma_f32_16x16x32_bf16 v[6:9], v[182:185], v[222:225], v[6:9]
	v_mfma_f32_16x16x32_bf16 v[2:5], v[190:193], v[222:225], v[2:5]
	v_mfma_f32_16x16x32_bf16 v[54:57], v[186:189], v[202:205], v[54:57]
	v_mfma_f32_16x16x32_bf16 v[50:53], v[194:197], v[202:205], v[50:53]
	v_mfma_f32_16x16x32_bf16 v[38:41], v[186:189], v[210:213], v[38:41]
	v_mfma_f32_16x16x32_bf16 v[30:33], v[194:197], v[210:213], v[30:33]
	v_mfma_f32_16x16x32_bf16 v[22:25], v[186:189], v[218:221], v[22:25]
	v_mfma_f32_16x16x32_bf16 v[14:17], v[194:197], v[218:221], v[14:17]
	v_mfma_f32_16x16x32_bf16 v[6:9], v[186:189], v[226:229], v[6:9]
	v_mfma_f32_16x16x32_bf16 v[2:5], v[194:197], v[226:229], v[2:5]
	s_setprio 0
	s_barrier
	s_add_i32 s52, 0, 0x18000
	s_add_i32 s53, 0, 0x1c000
	v_add_u32_e32 v170, s52, v176
	v_add_u32_e32 v181, s53, v176
	ds_read_b128 v[158:161], v170
	ds_read_b128 v[162:165], v170 offset:1024
	ds_read_b128 v[166:169], v170 offset:2048
	ds_read_b128 v[170:173], v170 offset:3072
	ds_read_b128 v[182:185], v181
	ds_read_b128 v[186:189], v181 offset:1024
	ds_read_b128 v[190:193], v181 offset:2048
	ds_read_b128 v[194:197], v181 offset:3072
	s_add_u32 s16, s22, 0xb0000
	s_addc_u32 s17, s23, 0
	s_mov_b32 m0, s31
	v_lshl_add_u64 v[236:237], s[16:17], 0, v[130:131]
	ds_read_b128 v[198:201], v180 offset:32768
	ds_read_b128 v[202:205], v180 offset:33792
	ds_read_b128 v[206:209], v180 offset:34816
	ds_read_b128 v[210:213], v180 offset:35840
	ds_read_b128 v[214:217], v180 offset:36864
	ds_read_b128 v[218:221], v180 offset:37888
	ds_read_b128 v[222:225], v180 offset:38912
	ds_read_b128 v[226:229], v180 offset:39936
	global_load_lds_dwordx4 v[236:237], off
	s_mov_b32 m0, s33
	v_lshl_add_u64 v[236:237], s[16:17], 0, v[132:133]
	global_load_lds_dwordx4 v[236:237], off
	s_waitcnt vmcnt(8)
	s_waitcnt lgkmcnt(0)
	s_barrier
	s_setprio 1
	s_waitcnt lgkmcnt(0)
	v_mfma_f32_16x16x32_bf16 v[126:129], v[158:161], v[198:201], v[126:129]
	v_mfma_f32_16x16x32_bf16 v[122:125], v[166:169], v[198:201], v[122:125]
	v_mfma_f32_16x16x32_bf16 v[114:117], v[158:161], v[206:209], v[114:117]
	v_mfma_f32_16x16x32_bf16 v[106:109], v[166:169], v[206:209], v[106:109]
	v_mfma_f32_16x16x32_bf16 v[98:101], v[158:161], v[214:217], v[98:101]
	v_mfma_f32_16x16x32_bf16 v[90:93], v[166:169], v[214:217], v[90:93]
	v_mfma_f32_16x16x32_bf16 v[78:81], v[158:161], v[222:225], v[78:81]
	v_mfma_f32_16x16x32_bf16 v[74:77], v[166:169], v[222:225], v[74:77]
	v_mfma_f32_16x16x32_bf16 v[126:129], v[162:165], v[202:205], v[126:129]
	v_mfma_f32_16x16x32_bf16 v[122:125], v[170:173], v[202:205], v[122:125]
	v_mfma_f32_16x16x32_bf16 v[114:117], v[162:165], v[210:213], v[114:117]
	v_mfma_f32_16x16x32_bf16 v[106:109], v[170:173], v[210:213], v[106:109]
	v_mfma_f32_16x16x32_bf16 v[98:101], v[162:165], v[218:221], v[98:101]
	v_mfma_f32_16x16x32_bf16 v[90:93], v[170:173], v[218:221], v[90:93]
	v_mfma_f32_16x16x32_bf16 v[78:81], v[162:165], v[226:229], v[78:81]
	v_mfma_f32_16x16x32_bf16 v[74:77], v[170:173], v[226:229], v[74:77]
	s_setprio 0
	s_setprio 1
	v_mfma_f32_16x16x32_bf16 v[118:121], v[182:185], v[198:201], v[118:121]
	v_mfma_f32_16x16x32_bf16 v[110:113], v[190:193], v[198:201], v[110:113]
	v_mfma_f32_16x16x32_bf16 v[102:105], v[182:185], v[206:209], v[102:105]
	v_mfma_f32_16x16x32_bf16 v[94:97], v[190:193], v[206:209], v[94:97]
	v_mfma_f32_16x16x32_bf16 v[86:89], v[182:185], v[214:217], v[86:89]
	v_mfma_f32_16x16x32_bf16 v[82:85], v[190:193], v[214:217], v[82:85]
	v_mfma_f32_16x16x32_bf16 v[70:73], v[182:185], v[222:225], v[70:73]
	v_mfma_f32_16x16x32_bf16 v[66:69], v[190:193], v[222:225], v[66:69]
	v_mfma_f32_16x16x32_bf16 v[118:121], v[186:189], v[202:205], v[118:121]
	v_mfma_f32_16x16x32_bf16 v[110:113], v[194:197], v[202:205], v[110:113]
	v_mfma_f32_16x16x32_bf16 v[102:105], v[186:189], v[210:213], v[102:105]
	v_mfma_f32_16x16x32_bf16 v[94:97], v[194:197], v[210:213], v[94:97]
	v_mfma_f32_16x16x32_bf16 v[86:89], v[186:189], v[218:221], v[86:89]
	v_mfma_f32_16x16x32_bf16 v[82:85], v[194:197], v[218:221], v[82:85]
	v_mfma_f32_16x16x32_bf16 v[70:73], v[186:189], v[226:229], v[70:73]
	v_mfma_f32_16x16x32_bf16 v[66:69], v[194:197], v[226:229], v[66:69]
	s_setprio 0
	s_barrier
	s_add_i32 s16, s52, s28
	v_lshl_add_u64 v[174:175], v[174:175], 0, s[10:11]
	s_mov_b32 m0, s16
	ds_read_b128 v[198:201], v180 offset:49152
	ds_read_b128 v[202:205], v180 offset:50176
	ds_read_b128 v[206:209], v180 offset:51200
	ds_read_b128 v[210:213], v180 offset:52224
	ds_read_b128 v[214:217], v180 offset:53248
	ds_read_b128 v[218:221], v180 offset:54272
	ds_read_b128 v[222:225], v180 offset:55296
	ds_read_b128 v[226:229], v180 offset:56320
	global_load_lds_dwordx4 v[174:175], off
	s_add_i32 m0, s16, 0x2000
	s_add_u32 s16, s20, 0xb0080
	v_lshl_add_u64 v[174:175], v[230:231], 0, s[10:11]
	s_addc_u32 s17, s21, 0
	s_add_i32 s20, s53, s28
	global_load_lds_dwordx4 v[174:175], off
	s_mov_b32 m0, s20
	v_lshl_add_u64 v[174:175], s[16:17], 0, v[130:131]
	global_load_lds_dwordx4 v[174:175], off
	s_add_i32 m0, s20, 0x2000
	v_lshl_add_u64 v[174:175], s[16:17], 0, v[132:133]
	global_load_lds_dwordx4 v[174:175], off
	s_mov_b32 m0, s39
	v_lshl_add_u64 v[174:175], v[232:233], 0, s[10:11]
	global_load_lds_dwordx4 v[174:175], off
	s_mov_b32 m0, s40
	v_lshl_add_u64 v[174:175], v[234:235], 0, s[10:11]
	global_load_lds_dwordx4 v[174:175], off
	s_waitcnt vmcnt(8)
	s_waitcnt lgkmcnt(0)
	s_barrier
	s_setprio 1
	s_waitcnt lgkmcnt(0)
	v_mfma_f32_16x16x32_bf16 v[62:65], v[158:161], v[198:201], v[62:65]
	v_mfma_f32_16x16x32_bf16 v[58:61], v[166:169], v[198:201], v[58:61]
	v_mfma_f32_16x16x32_bf16 v[46:49], v[158:161], v[206:209], v[46:49]
	v_mfma_f32_16x16x32_bf16 v[42:45], v[166:169], v[206:209], v[42:45]
	v_mfma_f32_16x16x32_bf16 v[34:37], v[158:161], v[214:217], v[34:37]
	v_mfma_f32_16x16x32_bf16 v[26:29], v[166:169], v[214:217], v[26:29]
	v_mfma_f32_16x16x32_bf16 v[18:21], v[158:161], v[222:225], v[18:21]
	v_mfma_f32_16x16x32_bf16 v[10:13], v[166:169], v[222:225], v[10:13]
	v_mfma_f32_16x16x32_bf16 v[62:65], v[162:165], v[202:205], v[62:65]
	v_mfma_f32_16x16x32_bf16 v[58:61], v[170:173], v[202:205], v[58:61]
	v_mfma_f32_16x16x32_bf16 v[46:49], v[162:165], v[210:213], v[46:49]
	v_mfma_f32_16x16x32_bf16 v[42:45], v[170:173], v[210:213], v[42:45]
	v_mfma_f32_16x16x32_bf16 v[34:37], v[162:165], v[218:221], v[34:37]
	v_mfma_f32_16x16x32_bf16 v[26:29], v[170:173], v[218:221], v[26:29]
	v_mfma_f32_16x16x32_bf16 v[18:21], v[162:165], v[226:229], v[18:21]
	v_mfma_f32_16x16x32_bf16 v[10:13], v[170:173], v[226:229], v[10:13]
	s_setprio 0
	s_setprio 1
	v_mfma_f32_16x16x32_bf16 v[54:57], v[182:185], v[198:201], v[54:57]
	v_mfma_f32_16x16x32_bf16 v[50:53], v[190:193], v[198:201], v[50:53]
	v_mfma_f32_16x16x32_bf16 v[38:41], v[182:185], v[206:209], v[38:41]
	v_mfma_f32_16x16x32_bf16 v[30:33], v[190:193], v[206:209], v[30:33]
	v_mfma_f32_16x16x32_bf16 v[22:25], v[182:185], v[214:217], v[22:25]
	v_mfma_f32_16x16x32_bf16 v[14:17], v[190:193], v[214:217], v[14:17]
	v_mfma_f32_16x16x32_bf16 v[6:9], v[182:185], v[222:225], v[6:9]
	v_mfma_f32_16x16x32_bf16 v[2:5], v[190:193], v[222:225], v[2:5]
	v_mfma_f32_16x16x32_bf16 v[54:57], v[186:189], v[202:205], v[54:57]
	v_mfma_f32_16x16x32_bf16 v[50:53], v[194:197], v[202:205], v[50:53]
	v_mfma_f32_16x16x32_bf16 v[38:41], v[186:189], v[210:213], v[38:41]
	v_mfma_f32_16x16x32_bf16 v[30:33], v[194:197], v[210:213], v[30:33]
	v_mfma_f32_16x16x32_bf16 v[22:25], v[186:189], v[218:221], v[22:25]
	v_mfma_f32_16x16x32_bf16 v[14:17], v[194:197], v[218:221], v[14:17]
	v_mfma_f32_16x16x32_bf16 v[6:9], v[186:189], v[226:229], v[6:9]
	v_mfma_f32_16x16x32_bf16 v[2:5], v[194:197], v[226:229], v[2:5]
	s_setprio 0
	s_barrier
	s_add_i32 s51, s51, 2
	s_add_u32 s2, s2, 0x100
	s_addc_u32 s50, s50, 0
	s_cmp_gt_u32 s51, 41
	s_mov_b64 s[16:17], s[18:19]
	s_cbranch_scc0 .LBB0_2583
	s_and_b64 vcc, exec, s[12:13]
	s_cbranch_vccz .LBB0_2586
	s_barrier
